# LayerNorm rows hand-scheduled: gamma/beta once per item, all 8 rows of a wave requested up front, counted waits, readlane cross-row reduction
# speedup vs baseline: 1.0061x; 1.0061x over previous
.LBB0_64:
	v_lshlrev_b32_e32 v212, 4, v219
	v_lshlrev_b32_e32 v214, 3, v219
	v_readfirstlane_b32 s42, v32
	v_readfirstlane_b32 s43, v33
	v_readfirstlane_b32 s66, v30
	v_readfirstlane_b32 s67, v31
	global_load_dwordx4 v[184:187], v[26:27], off offset:0
	global_load_dwordx4 v[188:191], v[26:27], off offset:1024
	global_load_dwordx4 v[192:195], v[26:27], off offset:2048
	global_load_dwordx4 v[196:199], v[26:27], off offset:3072
	global_load_dwordx4 v[200:203], v[28:29], off offset:0
	global_load_dwordx4 v[204:207], v[28:29], off offset:1024
	global_load_dwordx4 v[226:229], v[28:29], off offset:2048
	global_load_dwordx4 v[230:233], v[28:29], off offset:3072
	s_sub_u32 s42, s42, 0x1000
	s_subb_u32 s43, s43, 0
	global_load_dwordx4 v[2:5], v212, s[42:43] offset:0
	global_load_dwordx4 v[6:9], v212, s[42:43] offset:1024
	global_load_dwordx4 v[10:13], v212, s[42:43] offset:2048
	global_load_dwordx4 v[14:17], v212, s[42:43] offset:3072
	s_add_u32 s44, s42, 0x1000
	s_addc_u32 s45, s43, 0
	global_load_dwordx4 v[18:21], v212, s[44:45] offset:0
	global_load_dwordx4 v[22:25], v212, s[44:45] offset:1024
	global_load_dwordx4 v[34:37], v212, s[44:45] offset:2048
	global_load_dwordx4 v[38:41], v212, s[44:45] offset:3072
	s_add_u32 s46, s44, 0x1000
	s_addc_u32 s47, s45, 0
	global_load_dwordx4 v[44:47], v212, s[46:47] offset:0
	global_load_dwordx4 v[48:51], v212, s[46:47] offset:1024
	global_load_dwordx4 v[52:55], v212, s[46:47] offset:2048
	global_load_dwordx4 v[56:59], v212, s[46:47] offset:3072
	s_add_u32 s48, s46, 0x1000
	s_addc_u32 s49, s47, 0
	global_load_dwordx4 v[60:63], v212, s[48:49] offset:0
	global_load_dwordx4 v[64:67], v212, s[48:49] offset:1024
	global_load_dwordx4 v[94:97], v212, s[48:49] offset:2048
	global_load_dwordx4 v[98:101], v212, s[48:49] offset:3072
	s_add_u32 s50, s48, 0x1000
	s_addc_u32 s51, s49, 0
	global_load_dwordx4 v[102:105], v212, s[50:51] offset:0
	global_load_dwordx4 v[106:109], v212, s[50:51] offset:1024
	global_load_dwordx4 v[110:113], v212, s[50:51] offset:2048
	global_load_dwordx4 v[114:117], v212, s[50:51] offset:3072
	s_add_u32 s52, s50, 0x1000
	s_addc_u32 s53, s51, 0
	global_load_dwordx4 v[118:121], v212, s[52:53] offset:0
	global_load_dwordx4 v[122:125], v212, s[52:53] offset:1024
	global_load_dwordx4 v[144:147], v212, s[52:53] offset:2048
	global_load_dwordx4 v[148:151], v212, s[52:53] offset:3072
	s_add_u32 s62, s52, 0x1000
	s_addc_u32 s63, s53, 0
	global_load_dwordx4 v[152:155], v212, s[62:63] offset:0
	global_load_dwordx4 v[156:159], v212, s[62:63] offset:1024
	global_load_dwordx4 v[160:163], v212, s[62:63] offset:2048
	global_load_dwordx4 v[164:167], v212, s[62:63] offset:3072
	s_add_u32 s64, s62, 0x1000
	s_addc_u32 s65, s63, 0
	global_load_dwordx4 v[168:171], v212, s[64:65] offset:0
	global_load_dwordx4 v[172:175], v212, s[64:65] offset:1024
	global_load_dwordx4 v[176:179], v212, s[64:65] offset:2048
	global_load_dwordx4 v[180:183], v212, s[64:65] offset:3072
	s_add_u32 s66, s66, 0x1f80000
	s_addc_u32 s67, s67, 0
	s_add_u32 s68, s66, 0x1000
	s_addc_u32 s69, s67, 0
	s_add_u32 s70, s68, 0x1000
	s_addc_u32 s71, s69, 0
	s_add_u32 s72, s70, 0x1000
	s_addc_u32 s73, s71, 0
	s_waitcnt vmcnt(28)
	v_pk_add_f32 v[76:77], v[2:3], v[4:5]
	v_pk_add_f32 v[136:137], v[6:7], v[8:9]
	v_pk_add_f32 v[138:139], v[10:11], v[12:13]
	v_pk_add_f32 v[208:209], v[14:15], v[16:17]
	v_pk_add_f32 v[76:77], v[76:77], v[136:137]
	v_pk_add_f32 v[138:139], v[138:139], v[208:209]
	v_pk_add_f32 v[76:77], v[76:77], v[138:139]
	v_add_f32_e32 v131, v76, v77
	s_nop 1
	v_add_f32_dpp v131, v131, v131 quad_perm:[1,0,3,2] row_mask:0xf bank_mask:0xf bound_ctrl:1
	s_nop 1
	v_add_f32_dpp v131, v131, v131 quad_perm:[2,3,0,1] row_mask:0xf bank_mask:0xf bound_ctrl:1
	s_nop 1
	v_add_f32_dpp v131, v131, v131 row_half_mirror row_mask:0xf bank_mask:0xf bound_ctrl:1
	s_nop 1
	v_add_f32_dpp v131, v131, v131 row_mirror row_mask:0xf bank_mask:0xf bound_ctrl:1
	s_nop 1
	v_readlane_b32 s56, v131, 0
	v_readlane_b32 s57, v131, 16
	v_readlane_b32 s58, v131, 32
	v_readlane_b32 s59, v131, 48
	v_mov_b32_e32 v222, s57
	v_mov_b32_e32 v223, s59
	v_add_f32_e32 v222, s56, v222
	v_add_f32_e32 v223, s58, v223
	v_add_f32_e32 v131, v222, v223
	v_mul_f32_e32 v216, 0x3a800000, v131
	v_pk_add_f32 v[2:3], v[2:3], v[216:217] op_sel_hi:[1,0] neg_lo:[0,1] neg_hi:[0,1]
	v_pk_add_f32 v[4:5], v[4:5], v[216:217] op_sel_hi:[1,0] neg_lo:[0,1] neg_hi:[0,1]
	v_pk_add_f32 v[6:7], v[6:7], v[216:217] op_sel_hi:[1,0] neg_lo:[0,1] neg_hi:[0,1]
	v_pk_add_f32 v[8:9], v[8:9], v[216:217] op_sel_hi:[1,0] neg_lo:[0,1] neg_hi:[0,1]
	v_pk_add_f32 v[10:11], v[10:11], v[216:217] op_sel_hi:[1,0] neg_lo:[0,1] neg_hi:[0,1]
	v_pk_add_f32 v[12:13], v[12:13], v[216:217] op_sel_hi:[1,0] neg_lo:[0,1] neg_hi:[0,1]
	v_pk_add_f32 v[14:15], v[14:15], v[216:217] op_sel_hi:[1,0] neg_lo:[0,1] neg_hi:[0,1]
	v_pk_add_f32 v[16:17], v[16:17], v[216:217] op_sel_hi:[1,0] neg_lo:[0,1] neg_hi:[0,1]
	v_pk_mul_f32 v[76:77], v[2:3], v[2:3]
	v_pk_mul_f32 v[136:137], v[4:5], v[4:5]
	v_add_f32_e32 v133, v76, v77
	v_add_f32_e32 v133, v136, v133
	v_add_f32_e32 v133, v137, v133
	v_pk_mul_f32 v[76:77], v[6:7], v[6:7]
	v_pk_mul_f32 v[136:137], v[8:9], v[8:9]
	v_add_f32_e32 v133, v76, v133
	v_add_f32_e32 v133, v77, v133
	v_add_f32_e32 v133, v136, v133
	v_add_f32_e32 v133, v137, v133
	v_pk_mul_f32 v[76:77], v[10:11], v[10:11]
	v_pk_mul_f32 v[136:137], v[12:13], v[12:13]
	v_add_f32_e32 v133, v76, v133
	v_add_f32_e32 v133, v77, v133
	v_add_f32_e32 v133, v136, v133
	v_add_f32_e32 v133, v137, v133
	v_pk_mul_f32 v[76:77], v[14:15], v[14:15]
	v_pk_mul_f32 v[136:137], v[16:17], v[16:17]
	v_add_f32_e32 v133, v76, v133
	v_add_f32_e32 v133, v77, v133
	v_add_f32_e32 v133, v136, v133
	v_add_f32_e32 v133, v137, v133
	s_nop 1
	v_add_f32_dpp v133, v133, v133 quad_perm:[1,0,3,2] row_mask:0xf bank_mask:0xf bound_ctrl:1
	s_nop 1
	v_add_f32_dpp v133, v133, v133 quad_perm:[2,3,0,1] row_mask:0xf bank_mask:0xf bound_ctrl:1
	s_nop 1
	v_add_f32_dpp v133, v133, v133 row_half_mirror row_mask:0xf bank_mask:0xf bound_ctrl:1
	s_nop 1
	v_add_f32_dpp v133, v133, v133 row_mirror row_mask:0xf bank_mask:0xf bound_ctrl:1
	s_nop 1
	v_readlane_b32 s56, v133, 0
	v_readlane_b32 s57, v133, 16
	v_readlane_b32 s58, v133, 32
	v_readlane_b32 s59, v133, 48
	v_mov_b32_e32 v222, s57
	v_mov_b32_e32 v223, s59
	v_add_f32_e32 v222, s56, v222
	v_add_f32_e32 v223, s58, v223
	v_add_f32_e32 v133, v222, v223
	v_fmamk_f32 v133, v133, 0x3a800000, v215
	v_cmp_gt_f32_e32 vcc, s33, v133
	v_mul_f32_e32 v222, 0x4b800000, v133
	s_nop 0
	v_cndmask_b32_e32 v133, v133, v222, vcc
	v_rsq_f32_e32 v133, v133
	s_nop 0
	v_mul_f32_e32 v222, 0x45800000, v133
	v_cndmask_b32_e32 v220, v133, v222, vcc
	v_pk_mul_f32 v[2:3], v[2:3], v[220:221] op_sel_hi:[1,0]
	v_pk_mul_f32 v[4:5], v[4:5], v[220:221] op_sel_hi:[1,0]
	v_pk_mul_f32 v[6:7], v[6:7], v[220:221] op_sel_hi:[1,0]
	v_pk_mul_f32 v[8:9], v[8:9], v[220:221] op_sel_hi:[1,0]
	v_pk_mul_f32 v[10:11], v[10:11], v[220:221] op_sel_hi:[1,0]
	v_pk_mul_f32 v[12:13], v[12:13], v[220:221] op_sel_hi:[1,0]
	v_pk_mul_f32 v[14:15], v[14:15], v[220:221] op_sel_hi:[1,0]
	v_pk_mul_f32 v[16:17], v[16:17], v[220:221] op_sel_hi:[1,0]
	v_pk_fma_f32 v[2:3], v[184:185], v[2:3], v[200:201]
	v_pk_fma_f32 v[4:5], v[186:187], v[4:5], v[202:203]
	v_pk_fma_f32 v[6:7], v[188:189], v[6:7], v[204:205]
	v_pk_fma_f32 v[8:9], v[190:191], v[8:9], v[206:207]
	v_pk_fma_f32 v[10:11], v[192:193], v[10:11], v[226:227]
	v_pk_fma_f32 v[12:13], v[194:195], v[12:13], v[228:229]
	v_pk_fma_f32 v[14:15], v[196:197], v[14:15], v[230:231]
	v_pk_fma_f32 v[16:17], v[198:199], v[16:17], v[232:233]
	global_store_dwordx4 v212, v[2:5], s[42:43] offset:0
	global_store_dwordx4 v212, v[6:9], s[42:43] offset:1024
	global_store_dwordx4 v212, v[10:13], s[42:43] offset:2048
	global_store_dwordx4 v212, v[14:17], s[42:43] offset:3072
	v_cvt_pk_bf16_f32 v2, v2, v3
	v_cvt_pk_bf16_f32 v3, v4, v5
	v_cvt_pk_bf16_f32 v6, v6, v7
	v_cvt_pk_bf16_f32 v7, v8, v9
	v_cvt_pk_bf16_f32 v10, v10, v11
	v_cvt_pk_bf16_f32 v11, v12, v13
	v_cvt_pk_bf16_f32 v14, v14, v15
	v_cvt_pk_bf16_f32 v15, v16, v17
	global_store_dwordx2 v214, v[2:3], s[66:67] offset:0
	global_store_dwordx2 v214, v[6:7], s[66:67] offset:512
	global_store_dwordx2 v214, v[10:11], s[66:67] offset:1024
	global_store_dwordx2 v214, v[14:15], s[66:67] offset:1536
	s_waitcnt vmcnt(32)
	v_pk_add_f32 v[76:77], v[18:19], v[20:21]
	v_pk_add_f32 v[136:137], v[22:23], v[24:25]
	v_pk_add_f32 v[138:139], v[34:35], v[36:37]
	v_pk_add_f32 v[208:209], v[38:39], v[40:41]
	v_pk_add_f32 v[76:77], v[76:77], v[136:137]
	v_pk_add_f32 v[138:139], v[138:139], v[208:209]
	v_pk_add_f32 v[76:77], v[76:77], v[138:139]
	v_add_f32_e32 v131, v76, v77
	s_nop 1
	v_add_f32_dpp v131, v131, v131 quad_perm:[1,0,3,2] row_mask:0xf bank_mask:0xf bound_ctrl:1
	s_nop 1
	v_add_f32_dpp v131, v131, v131 quad_perm:[2,3,0,1] row_mask:0xf bank_mask:0xf bound_ctrl:1
	s_nop 1
	v_add_f32_dpp v131, v131, v131 row_half_mirror row_mask:0xf bank_mask:0xf bound_ctrl:1
	s_nop 1
	v_add_f32_dpp v131, v131, v131 row_mirror row_mask:0xf bank_mask:0xf bound_ctrl:1
	s_nop 1
	v_readlane_b32 s56, v131, 0
	v_readlane_b32 s57, v131, 16
	v_readlane_b32 s58, v131, 32
	v_readlane_b32 s59, v131, 48
	v_mov_b32_e32 v222, s57
	v_mov_b32_e32 v223, s59
	v_add_f32_e32 v222, s56, v222
	v_add_f32_e32 v223, s58, v223
	v_add_f32_e32 v131, v222, v223
	v_mul_f32_e32 v216, 0x3a800000, v131
	v_pk_add_f32 v[18:19], v[18:19], v[216:217] op_sel_hi:[1,0] neg_lo:[0,1] neg_hi:[0,1]
	v_pk_add_f32 v[20:21], v[20:21], v[216:217] op_sel_hi:[1,0] neg_lo:[0,1] neg_hi:[0,1]
	v_pk_add_f32 v[22:23], v[22:23], v[216:217] op_sel_hi:[1,0] neg_lo:[0,1] neg_hi:[0,1]
	v_pk_add_f32 v[24:25], v[24:25], v[216:217] op_sel_hi:[1,0] neg_lo:[0,1] neg_hi:[0,1]
	v_pk_add_f32 v[34:35], v[34:35], v[216:217] op_sel_hi:[1,0] neg_lo:[0,1] neg_hi:[0,1]
	v_pk_add_f32 v[36:37], v[36:37], v[216:217] op_sel_hi:[1,0] neg_lo:[0,1] neg_hi:[0,1]
	v_pk_add_f32 v[38:39], v[38:39], v[216:217] op_sel_hi:[1,0] neg_lo:[0,1] neg_hi:[0,1]
	v_pk_add_f32 v[40:41], v[40:41], v[216:217] op_sel_hi:[1,0] neg_lo:[0,1] neg_hi:[0,1]
	v_pk_mul_f32 v[76:77], v[18:19], v[18:19]
	v_pk_mul_f32 v[136:137], v[20:21], v[20:21]
	v_add_f32_e32 v133, v76, v77
	v_add_f32_e32 v133, v136, v133
	v_add_f32_e32 v133, v137, v133
	v_pk_mul_f32 v[76:77], v[22:23], v[22:23]
	v_pk_mul_f32 v[136:137], v[24:25], v[24:25]
	v_add_f32_e32 v133, v76, v133
	v_add_f32_e32 v133, v77, v133
	v_add_f32_e32 v133, v136, v133
	v_add_f32_e32 v133, v137, v133
	v_pk_mul_f32 v[76:77], v[34:35], v[34:35]
	v_pk_mul_f32 v[136:137], v[36:37], v[36:37]
	v_add_f32_e32 v133, v76, v133
	v_add_f32_e32 v133, v77, v133
	v_add_f32_e32 v133, v136, v133
	v_add_f32_e32 v133, v137, v133
	v_pk_mul_f32 v[76:77], v[38:39], v[38:39]
	v_pk_mul_f32 v[136:137], v[40:41], v[40:41]
	v_add_f32_e32 v133, v76, v133
	v_add_f32_e32 v133, v77, v133
	v_add_f32_e32 v133, v136, v133
	v_add_f32_e32 v133, v137, v133
	s_nop 1
	v_add_f32_dpp v133, v133, v133 quad_perm:[1,0,3,2] row_mask:0xf bank_mask:0xf bound_ctrl:1
	s_nop 1
	v_add_f32_dpp v133, v133, v133 quad_perm:[2,3,0,1] row_mask:0xf bank_mask:0xf bound_ctrl:1
	s_nop 1
	v_add_f32_dpp v133, v133, v133 row_half_mirror row_mask:0xf bank_mask:0xf bound_ctrl:1
	s_nop 1
	v_add_f32_dpp v133, v133, v133 row_mirror row_mask:0xf bank_mask:0xf bound_ctrl:1
	s_nop 1
	v_readlane_b32 s56, v133, 0
	v_readlane_b32 s57, v133, 16
	v_readlane_b32 s58, v133, 32
	v_readlane_b32 s59, v133, 48
	v_mov_b32_e32 v222, s57
	v_mov_b32_e32 v223, s59
	v_add_f32_e32 v222, s56, v222
	v_add_f32_e32 v223, s58, v223
	v_add_f32_e32 v133, v222, v223
	v_fmamk_f32 v133, v133, 0x3a800000, v215
	v_cmp_gt_f32_e32 vcc, s33, v133
	v_mul_f32_e32 v222, 0x4b800000, v133
	s_nop 0
	v_cndmask_b32_e32 v133, v133, v222, vcc
	v_rsq_f32_e32 v133, v133
	s_nop 0
	v_mul_f32_e32 v222, 0x45800000, v133
	v_cndmask_b32_e32 v220, v133, v222, vcc
	v_pk_mul_f32 v[18:19], v[18:19], v[220:221] op_sel_hi:[1,0]
	v_pk_mul_f32 v[20:21], v[20:21], v[220:221] op_sel_hi:[1,0]
	v_pk_mul_f32 v[22:23], v[22:23], v[220:221] op_sel_hi:[1,0]
	v_pk_mul_f32 v[24:25], v[24:25], v[220:221] op_sel_hi:[1,0]
	v_pk_mul_f32 v[34:35], v[34:35], v[220:221] op_sel_hi:[1,0]
	v_pk_mul_f32 v[36:37], v[36:37], v[220:221] op_sel_hi:[1,0]
	v_pk_mul_f32 v[38:39], v[38:39], v[220:221] op_sel_hi:[1,0]
	v_pk_mul_f32 v[40:41], v[40:41], v[220:221] op_sel_hi:[1,0]
	v_pk_fma_f32 v[18:19], v[184:185], v[18:19], v[200:201]
	v_pk_fma_f32 v[20:21], v[186:187], v[20:21], v[202:203]
	v_pk_fma_f32 v[22:23], v[188:189], v[22:23], v[204:205]
	v_pk_fma_f32 v[24:25], v[190:191], v[24:25], v[206:207]
	v_pk_fma_f32 v[34:35], v[192:193], v[34:35], v[226:227]
	v_pk_fma_f32 v[36:37], v[194:195], v[36:37], v[228:229]
	v_pk_fma_f32 v[38:39], v[196:197], v[38:39], v[230:231]
	v_pk_fma_f32 v[40:41], v[198:199], v[40:41], v[232:233]
	global_store_dwordx4 v212, v[18:21], s[44:45] offset:0
	global_store_dwordx4 v212, v[22:25], s[44:45] offset:1024
	global_store_dwordx4 v212, v[34:37], s[44:45] offset:2048
	global_store_dwordx4 v212, v[38:41], s[44:45] offset:3072
	v_cvt_pk_bf16_f32 v18, v18, v19
	v_cvt_pk_bf16_f32 v19, v20, v21
	v_cvt_pk_bf16_f32 v22, v22, v23
	v_cvt_pk_bf16_f32 v23, v24, v25
	v_cvt_pk_bf16_f32 v34, v34, v35
	v_cvt_pk_bf16_f32 v35, v36, v37
	v_cvt_pk_bf16_f32 v38, v38, v39
	v_cvt_pk_bf16_f32 v39, v40, v41
	global_store_dwordx2 v214, v[18:19], s[66:67] offset:2048
	global_store_dwordx2 v214, v[22:23], s[66:67] offset:2560
	global_store_dwordx2 v214, v[34:35], s[66:67] offset:3072
	global_store_dwordx2 v214, v[38:39], s[66:67] offset:3584
	s_waitcnt vmcnt(36)
	v_pk_add_f32 v[76:77], v[44:45], v[46:47]
	v_pk_add_f32 v[136:137], v[48:49], v[50:51]
	v_pk_add_f32 v[138:139], v[52:53], v[54:55]
	v_pk_add_f32 v[208:209], v[56:57], v[58:59]
	v_pk_add_f32 v[76:77], v[76:77], v[136:137]
	v_pk_add_f32 v[138:139], v[138:139], v[208:209]
	v_pk_add_f32 v[76:77], v[76:77], v[138:139]
	v_add_f32_e32 v131, v76, v77
	s_nop 1
	v_add_f32_dpp v131, v131, v131 quad_perm:[1,0,3,2] row_mask:0xf bank_mask:0xf bound_ctrl:1
	s_nop 1
	v_add_f32_dpp v131, v131, v131 quad_perm:[2,3,0,1] row_mask:0xf bank_mask:0xf bound_ctrl:1
	s_nop 1
	v_add_f32_dpp v131, v131, v131 row_half_mirror row_mask:0xf bank_mask:0xf bound_ctrl:1
	s_nop 1
	v_add_f32_dpp v131, v131, v131 row_mirror row_mask:0xf bank_mask:0xf bound_ctrl:1
	s_nop 1
	v_readlane_b32 s56, v131, 0
	v_readlane_b32 s57, v131, 16
	v_readlane_b32 s58, v131, 32
	v_readlane_b32 s59, v131, 48
	v_mov_b32_e32 v222, s57
	v_mov_b32_e32 v223, s59
	v_add_f32_e32 v222, s56, v222
	v_add_f32_e32 v223, s58, v223
	v_add_f32_e32 v131, v222, v223
	v_mul_f32_e32 v216, 0x3a800000, v131
	v_pk_add_f32 v[44:45], v[44:45], v[216:217] op_sel_hi:[1,0] neg_lo:[0,1] neg_hi:[0,1]
	v_pk_add_f32 v[46:47], v[46:47], v[216:217] op_sel_hi:[1,0] neg_lo:[0,1] neg_hi:[0,1]
	v_pk_add_f32 v[48:49], v[48:49], v[216:217] op_sel_hi:[1,0] neg_lo:[0,1] neg_hi:[0,1]
	v_pk_add_f32 v[50:51], v[50:51], v[216:217] op_sel_hi:[1,0] neg_lo:[0,1] neg_hi:[0,1]
	v_pk_add_f32 v[52:53], v[52:53], v[216:217] op_sel_hi:[1,0] neg_lo:[0,1] neg_hi:[0,1]
	v_pk_add_f32 v[54:55], v[54:55], v[216:217] op_sel_hi:[1,0] neg_lo:[0,1] neg_hi:[0,1]
	v_pk_add_f32 v[56:57], v[56:57], v[216:217] op_sel_hi:[1,0] neg_lo:[0,1] neg_hi:[0,1]
	v_pk_add_f32 v[58:59], v[58:59], v[216:217] op_sel_hi:[1,0] neg_lo:[0,1] neg_hi:[0,1]
	v_pk_mul_f32 v[76:77], v[44:45], v[44:45]
	v_pk_mul_f32 v[136:137], v[46:47], v[46:47]
	v_add_f32_e32 v133, v76, v77
	v_add_f32_e32 v133, v136, v133
	v_add_f32_e32 v133, v137, v133
	v_pk_mul_f32 v[76:77], v[48:49], v[48:49]
	v_pk_mul_f32 v[136:137], v[50:51], v[50:51]
	v_add_f32_e32 v133, v76, v133
	v_add_f32_e32 v133, v77, v133
	v_add_f32_e32 v133, v136, v133
	v_add_f32_e32 v133, v137, v133
	v_pk_mul_f32 v[76:77], v[52:53], v[52:53]
	v_pk_mul_f32 v[136:137], v[54:55], v[54:55]
	v_add_f32_e32 v133, v76, v133
	v_add_f32_e32 v133, v77, v133
	v_add_f32_e32 v133, v136, v133
	v_add_f32_e32 v133, v137, v133
	v_pk_mul_f32 v[76:77], v[56:57], v[56:57]
	v_pk_mul_f32 v[136:137], v[58:59], v[58:59]
	v_add_f32_e32 v133, v76, v133
	v_add_f32_e32 v133, v77, v133
	v_add_f32_e32 v133, v136, v133
	v_add_f32_e32 v133, v137, v133
	s_nop 1
	v_add_f32_dpp v133, v133, v133 quad_perm:[1,0,3,2] row_mask:0xf bank_mask:0xf bound_ctrl:1
	s_nop 1
	v_add_f32_dpp v133, v133, v133 quad_perm:[2,3,0,1] row_mask:0xf bank_mask:0xf bound_ctrl:1
	s_nop 1
	v_add_f32_dpp v133, v133, v133 row_half_mirror row_mask:0xf bank_mask:0xf bound_ctrl:1
	s_nop 1
	v_add_f32_dpp v133, v133, v133 row_mirror row_mask:0xf bank_mask:0xf bound_ctrl:1
	s_nop 1
	v_readlane_b32 s56, v133, 0
	v_readlane_b32 s57, v133, 16
	v_readlane_b32 s58, v133, 32
	v_readlane_b32 s59, v133, 48
	v_mov_b32_e32 v222, s57
	v_mov_b32_e32 v223, s59
	v_add_f32_e32 v222, s56, v222
	v_add_f32_e32 v223, s58, v223
	v_add_f32_e32 v133, v222, v223
	v_fmamk_f32 v133, v133, 0x3a800000, v215
	v_cmp_gt_f32_e32 vcc, s33, v133
	v_mul_f32_e32 v222, 0x4b800000, v133
	s_nop 0
	v_cndmask_b32_e32 v133, v133, v222, vcc
	v_rsq_f32_e32 v133, v133
	s_nop 0
	v_mul_f32_e32 v222, 0x45800000, v133
	v_cndmask_b32_e32 v220, v133, v222, vcc
	v_pk_mul_f32 v[44:45], v[44:45], v[220:221] op_sel_hi:[1,0]
	v_pk_mul_f32 v[46:47], v[46:47], v[220:221] op_sel_hi:[1,0]
	v_pk_mul_f32 v[48:49], v[48:49], v[220:221] op_sel_hi:[1,0]
	v_pk_mul_f32 v[50:51], v[50:51], v[220:221] op_sel_hi:[1,0]
	v_pk_mul_f32 v[52:53], v[52:53], v[220:221] op_sel_hi:[1,0]
	v_pk_mul_f32 v[54:55], v[54:55], v[220:221] op_sel_hi:[1,0]
	v_pk_mul_f32 v[56:57], v[56:57], v[220:221] op_sel_hi:[1,0]
	v_pk_mul_f32 v[58:59], v[58:59], v[220:221] op_sel_hi:[1,0]
	v_pk_fma_f32 v[44:45], v[184:185], v[44:45], v[200:201]
	v_pk_fma_f32 v[46:47], v[186:187], v[46:47], v[202:203]
	v_pk_fma_f32 v[48:49], v[188:189], v[48:49], v[204:205]
	v_pk_fma_f32 v[50:51], v[190:191], v[50:51], v[206:207]
	v_pk_fma_f32 v[52:53], v[192:193], v[52:53], v[226:227]
	v_pk_fma_f32 v[54:55], v[194:195], v[54:55], v[228:229]
	v_pk_fma_f32 v[56:57], v[196:197], v[56:57], v[230:231]
	v_pk_fma_f32 v[58:59], v[198:199], v[58:59], v[232:233]
	global_store_dwordx4 v212, v[44:47], s[46:47] offset:0
	global_store_dwordx4 v212, v[48:51], s[46:47] offset:1024
	global_store_dwordx4 v212, v[52:55], s[46:47] offset:2048
	global_store_dwordx4 v212, v[56:59], s[46:47] offset:3072
	v_cvt_pk_bf16_f32 v44, v44, v45
	v_cvt_pk_bf16_f32 v45, v46, v47
	v_cvt_pk_bf16_f32 v48, v48, v49
	v_cvt_pk_bf16_f32 v49, v50, v51
	v_cvt_pk_bf16_f32 v52, v52, v53
	v_cvt_pk_bf16_f32 v53, v54, v55
	v_cvt_pk_bf16_f32 v56, v56, v57
	v_cvt_pk_bf16_f32 v57, v58, v59
	global_store_dwordx2 v214, v[44:45], s[68:69] offset:0
	global_store_dwordx2 v214, v[48:49], s[68:69] offset:512
	global_store_dwordx2 v214, v[52:53], s[68:69] offset:1024
	global_store_dwordx2 v214, v[56:57], s[68:69] offset:1536
	s_waitcnt vmcnt(40)
	v_pk_add_f32 v[76:77], v[60:61], v[62:63]
	v_pk_add_f32 v[136:137], v[64:65], v[66:67]
	v_pk_add_f32 v[138:139], v[94:95], v[96:97]
	v_pk_add_f32 v[208:209], v[98:99], v[100:101]
	v_pk_add_f32 v[76:77], v[76:77], v[136:137]
	v_pk_add_f32 v[138:139], v[138:139], v[208:209]
	v_pk_add_f32 v[76:77], v[76:77], v[138:139]
	v_add_f32_e32 v131, v76, v77
	s_nop 1
	v_add_f32_dpp v131, v131, v131 quad_perm:[1,0,3,2] row_mask:0xf bank_mask:0xf bound_ctrl:1
	s_nop 1
	v_add_f32_dpp v131, v131, v131 quad_perm:[2,3,0,1] row_mask:0xf bank_mask:0xf bound_ctrl:1
	s_nop 1
	v_add_f32_dpp v131, v131, v131 row_half_mirror row_mask:0xf bank_mask:0xf bound_ctrl:1
	s_nop 1
	v_add_f32_dpp v131, v131, v131 row_mirror row_mask:0xf bank_mask:0xf bound_ctrl:1
	s_nop 1
	v_readlane_b32 s56, v131, 0
	v_readlane_b32 s57, v131, 16
	v_readlane_b32 s58, v131, 32
	v_readlane_b32 s59, v131, 48
	v_mov_b32_e32 v222, s57
	v_mov_b32_e32 v223, s59
	v_add_f32_e32 v222, s56, v222
	v_add_f32_e32 v223, s58, v223
	v_add_f32_e32 v131, v222, v223
	v_mul_f32_e32 v216, 0x3a800000, v131
	v_pk_add_f32 v[60:61], v[60:61], v[216:217] op_sel_hi:[1,0] neg_lo:[0,1] neg_hi:[0,1]
	v_pk_add_f32 v[62:63], v[62:63], v[216:217] op_sel_hi:[1,0] neg_lo:[0,1] neg_hi:[0,1]
	v_pk_add_f32 v[64:65], v[64:65], v[216:217] op_sel_hi:[1,0] neg_lo:[0,1] neg_hi:[0,1]
	v_pk_add_f32 v[66:67], v[66:67], v[216:217] op_sel_hi:[1,0] neg_lo:[0,1] neg_hi:[0,1]
	v_pk_add_f32 v[94:95], v[94:95], v[216:217] op_sel_hi:[1,0] neg_lo:[0,1] neg_hi:[0,1]
	v_pk_add_f32 v[96:97], v[96:97], v[216:217] op_sel_hi:[1,0] neg_lo:[0,1] neg_hi:[0,1]
	v_pk_add_f32 v[98:99], v[98:99], v[216:217] op_sel_hi:[1,0] neg_lo:[0,1] neg_hi:[0,1]
	v_pk_add_f32 v[100:101], v[100:101], v[216:217] op_sel_hi:[1,0] neg_lo:[0,1] neg_hi:[0,1]
	v_pk_mul_f32 v[76:77], v[60:61], v[60:61]
	v_pk_mul_f32 v[136:137], v[62:63], v[62:63]
	v_add_f32_e32 v133, v76, v77
	v_add_f32_e32 v133, v136, v133
	v_add_f32_e32 v133, v137, v133
	v_pk_mul_f32 v[76:77], v[64:65], v[64:65]
	v_pk_mul_f32 v[136:137], v[66:67], v[66:67]
	v_add_f32_e32 v133, v76, v133
	v_add_f32_e32 v133, v77, v133
	v_add_f32_e32 v133, v136, v133
	v_add_f32_e32 v133, v137, v133
	v_pk_mul_f32 v[76:77], v[94:95], v[94:95]
	v_pk_mul_f32 v[136:137], v[96:97], v[96:97]
	v_add_f32_e32 v133, v76, v133
	v_add_f32_e32 v133, v77, v133
	v_add_f32_e32 v133, v136, v133
	v_add_f32_e32 v133, v137, v133
	v_pk_mul_f32 v[76:77], v[98:99], v[98:99]
	v_pk_mul_f32 v[136:137], v[100:101], v[100:101]
	v_add_f32_e32 v133, v76, v133
	v_add_f32_e32 v133, v77, v133
	v_add_f32_e32 v133, v136, v133
	v_add_f32_e32 v133, v137, v133
	s_nop 1
	v_add_f32_dpp v133, v133, v133 quad_perm:[1,0,3,2] row_mask:0xf bank_mask:0xf bound_ctrl:1
	s_nop 1
	v_add_f32_dpp v133, v133, v133 quad_perm:[2,3,0,1] row_mask:0xf bank_mask:0xf bound_ctrl:1
	s_nop 1
	v_add_f32_dpp v133, v133, v133 row_half_mirror row_mask:0xf bank_mask:0xf bound_ctrl:1
	s_nop 1
	v_add_f32_dpp v133, v133, v133 row_mirror row_mask:0xf bank_mask:0xf bound_ctrl:1
	s_nop 1
	v_readlane_b32 s56, v133, 0
	v_readlane_b32 s57, v133, 16
	v_readlane_b32 s58, v133, 32
	v_readlane_b32 s59, v133, 48
	v_mov_b32_e32 v222, s57
	v_mov_b32_e32 v223, s59
	v_add_f32_e32 v222, s56, v222
	v_add_f32_e32 v223, s58, v223
	v_add_f32_e32 v133, v222, v223
	v_fmamk_f32 v133, v133, 0x3a800000, v215
	v_cmp_gt_f32_e32 vcc, s33, v133
	v_mul_f32_e32 v222, 0x4b800000, v133
	s_nop 0
	v_cndmask_b32_e32 v133, v133, v222, vcc
	v_rsq_f32_e32 v133, v133
	s_nop 0
	v_mul_f32_e32 v222, 0x45800000, v133
	v_cndmask_b32_e32 v220, v133, v222, vcc
	v_pk_mul_f32 v[60:61], v[60:61], v[220:221] op_sel_hi:[1,0]
	v_pk_mul_f32 v[62:63], v[62:63], v[220:221] op_sel_hi:[1,0]
	v_pk_mul_f32 v[64:65], v[64:65], v[220:221] op_sel_hi:[1,0]
	v_pk_mul_f32 v[66:67], v[66:67], v[220:221] op_sel_hi:[1,0]
	v_pk_mul_f32 v[94:95], v[94:95], v[220:221] op_sel_hi:[1,0]
	v_pk_mul_f32 v[96:97], v[96:97], v[220:221] op_sel_hi:[1,0]
	v_pk_mul_f32 v[98:99], v[98:99], v[220:221] op_sel_hi:[1,0]
	v_pk_mul_f32 v[100:101], v[100:101], v[220:221] op_sel_hi:[1,0]
	v_pk_fma_f32 v[60:61], v[184:185], v[60:61], v[200:201]
	v_pk_fma_f32 v[62:63], v[186:187], v[62:63], v[202:203]
	v_pk_fma_f32 v[64:65], v[188:189], v[64:65], v[204:205]
	v_pk_fma_f32 v[66:67], v[190:191], v[66:67], v[206:207]
	v_pk_fma_f32 v[94:95], v[192:193], v[94:95], v[226:227]
	v_pk_fma_f32 v[96:97], v[194:195], v[96:97], v[228:229]
	v_pk_fma_f32 v[98:99], v[196:197], v[98:99], v[230:231]
	v_pk_fma_f32 v[100:101], v[198:199], v[100:101], v[232:233]
	global_store_dwordx4 v212, v[60:63], s[48:49] offset:0
	global_store_dwordx4 v212, v[64:67], s[48:49] offset:1024
	global_store_dwordx4 v212, v[94:97], s[48:49] offset:2048
	global_store_dwordx4 v212, v[98:101], s[48:49] offset:3072
	v_cvt_pk_bf16_f32 v60, v60, v61
	v_cvt_pk_bf16_f32 v61, v62, v63
	v_cvt_pk_bf16_f32 v64, v64, v65
	v_cvt_pk_bf16_f32 v65, v66, v67
	v_cvt_pk_bf16_f32 v94, v94, v95
	v_cvt_pk_bf16_f32 v95, v96, v97
	v_cvt_pk_bf16_f32 v98, v98, v99
	v_cvt_pk_bf16_f32 v99, v100, v101
	global_store_dwordx2 v214, v[60:61], s[68:69] offset:2048
	global_store_dwordx2 v214, v[64:65], s[68:69] offset:2560
	global_store_dwordx2 v214, v[94:95], s[68:69] offset:3072
	global_store_dwordx2 v214, v[98:99], s[68:69] offset:3584
	s_waitcnt vmcnt(44)
	v_pk_add_f32 v[76:77], v[102:103], v[104:105]
	v_pk_add_f32 v[136:137], v[106:107], v[108:109]
	v_pk_add_f32 v[138:139], v[110:111], v[112:113]
	v_pk_add_f32 v[208:209], v[114:115], v[116:117]
	v_pk_add_f32 v[76:77], v[76:77], v[136:137]
	v_pk_add_f32 v[138:139], v[138:139], v[208:209]
	v_pk_add_f32 v[76:77], v[76:77], v[138:139]
	v_add_f32_e32 v131, v76, v77
	s_nop 1
	v_add_f32_dpp v131, v131, v131 quad_perm:[1,0,3,2] row_mask:0xf bank_mask:0xf bound_ctrl:1
	s_nop 1
	v_add_f32_dpp v131, v131, v131 quad_perm:[2,3,0,1] row_mask:0xf bank_mask:0xf bound_ctrl:1
	s_nop 1
	v_add_f32_dpp v131, v131, v131 row_half_mirror row_mask:0xf bank_mask:0xf bound_ctrl:1
	s_nop 1
	v_add_f32_dpp v131, v131, v131 row_mirror row_mask:0xf bank_mask:0xf bound_ctrl:1
	s_nop 1
	v_readlane_b32 s56, v131, 0
	v_readlane_b32 s57, v131, 16
	v_readlane_b32 s58, v131, 32
	v_readlane_b32 s59, v131, 48
	v_mov_b32_e32 v222, s57
	v_mov_b32_e32 v223, s59
	v_add_f32_e32 v222, s56, v222
	v_add_f32_e32 v223, s58, v223
	v_add_f32_e32 v131, v222, v223
	v_mul_f32_e32 v216, 0x3a800000, v131
	v_pk_add_f32 v[102:103], v[102:103], v[216:217] op_sel_hi:[1,0] neg_lo:[0,1] neg_hi:[0,1]
	v_pk_add_f32 v[104:105], v[104:105], v[216:217] op_sel_hi:[1,0] neg_lo:[0,1] neg_hi:[0,1]
	v_pk_add_f32 v[106:107], v[106:107], v[216:217] op_sel_hi:[1,0] neg_lo:[0,1] neg_hi:[0,1]
	v_pk_add_f32 v[108:109], v[108:109], v[216:217] op_sel_hi:[1,0] neg_lo:[0,1] neg_hi:[0,1]
	v_pk_add_f32 v[110:111], v[110:111], v[216:217] op_sel_hi:[1,0] neg_lo:[0,1] neg_hi:[0,1]
	v_pk_add_f32 v[112:113], v[112:113], v[216:217] op_sel_hi:[1,0] neg_lo:[0,1] neg_hi:[0,1]
	v_pk_add_f32 v[114:115], v[114:115], v[216:217] op_sel_hi:[1,0] neg_lo:[0,1] neg_hi:[0,1]
	v_pk_add_f32 v[116:117], v[116:117], v[216:217] op_sel_hi:[1,0] neg_lo:[0,1] neg_hi:[0,1]
	v_pk_mul_f32 v[76:77], v[102:103], v[102:103]
	v_pk_mul_f32 v[136:137], v[104:105], v[104:105]
	v_add_f32_e32 v133, v76, v77
	v_add_f32_e32 v133, v136, v133
	v_add_f32_e32 v133, v137, v133
	v_pk_mul_f32 v[76:77], v[106:107], v[106:107]
	v_pk_mul_f32 v[136:137], v[108:109], v[108:109]
	v_add_f32_e32 v133, v76, v133
	v_add_f32_e32 v133, v77, v133
	v_add_f32_e32 v133, v136, v133
	v_add_f32_e32 v133, v137, v133
	v_pk_mul_f32 v[76:77], v[110:111], v[110:111]
	v_pk_mul_f32 v[136:137], v[112:113], v[112:113]
	v_add_f32_e32 v133, v76, v133
	v_add_f32_e32 v133, v77, v133
	v_add_f32_e32 v133, v136, v133
	v_add_f32_e32 v133, v137, v133
	v_pk_mul_f32 v[76:77], v[114:115], v[114:115]
	v_pk_mul_f32 v[136:137], v[116:117], v[116:117]
	v_add_f32_e32 v133, v76, v133
	v_add_f32_e32 v133, v77, v133
	v_add_f32_e32 v133, v136, v133
	v_add_f32_e32 v133, v137, v133
	s_nop 1
	v_add_f32_dpp v133, v133, v133 quad_perm:[1,0,3,2] row_mask:0xf bank_mask:0xf bound_ctrl:1
	s_nop 1
	v_add_f32_dpp v133, v133, v133 quad_perm:[2,3,0,1] row_mask:0xf bank_mask:0xf bound_ctrl:1
	s_nop 1
	v_add_f32_dpp v133, v133, v133 row_half_mirror row_mask:0xf bank_mask:0xf bound_ctrl:1
	s_nop 1
	v_add_f32_dpp v133, v133, v133 row_mirror row_mask:0xf bank_mask:0xf bound_ctrl:1
	s_nop 1
	v_readlane_b32 s56, v133, 0
	v_readlane_b32 s57, v133, 16
	v_readlane_b32 s58, v133, 32
	v_readlane_b32 s59, v133, 48
	v_mov_b32_e32 v222, s57
	v_mov_b32_e32 v223, s59
	v_add_f32_e32 v222, s56, v222
	v_add_f32_e32 v223, s58, v223
	v_add_f32_e32 v133, v222, v223
	v_fmamk_f32 v133, v133, 0x3a800000, v215
	v_cmp_gt_f32_e32 vcc, s33, v133
	v_mul_f32_e32 v222, 0x4b800000, v133
	s_nop 0
	v_cndmask_b32_e32 v133, v133, v222, vcc
	v_rsq_f32_e32 v133, v133
	s_nop 0
	v_mul_f32_e32 v222, 0x45800000, v133
	v_cndmask_b32_e32 v220, v133, v222, vcc
	v_pk_mul_f32 v[102:103], v[102:103], v[220:221] op_sel_hi:[1,0]
	v_pk_mul_f32 v[104:105], v[104:105], v[220:221] op_sel_hi:[1,0]
	v_pk_mul_f32 v[106:107], v[106:107], v[220:221] op_sel_hi:[1,0]
	v_pk_mul_f32 v[108:109], v[108:109], v[220:221] op_sel_hi:[1,0]
	v_pk_mul_f32 v[110:111], v[110:111], v[220:221] op_sel_hi:[1,0]
	v_pk_mul_f32 v[112:113], v[112:113], v[220:221] op_sel_hi:[1,0]
	v_pk_mul_f32 v[114:115], v[114:115], v[220:221] op_sel_hi:[1,0]
	v_pk_mul_f32 v[116:117], v[116:117], v[220:221] op_sel_hi:[1,0]
	v_pk_fma_f32 v[102:103], v[184:185], v[102:103], v[200:201]
	v_pk_fma_f32 v[104:105], v[186:187], v[104:105], v[202:203]
	v_pk_fma_f32 v[106:107], v[188:189], v[106:107], v[204:205]
	v_pk_fma_f32 v[108:109], v[190:191], v[108:109], v[206:207]
	v_pk_fma_f32 v[110:111], v[192:193], v[110:111], v[226:227]
	v_pk_fma_f32 v[112:113], v[194:195], v[112:113], v[228:229]
	v_pk_fma_f32 v[114:115], v[196:197], v[114:115], v[230:231]
	v_pk_fma_f32 v[116:117], v[198:199], v[116:117], v[232:233]
	global_store_dwordx4 v212, v[102:105], s[50:51] offset:0
	global_store_dwordx4 v212, v[106:109], s[50:51] offset:1024
	global_store_dwordx4 v212, v[110:113], s[50:51] offset:2048
	global_store_dwordx4 v212, v[114:117], s[50:51] offset:3072
	v_cvt_pk_bf16_f32 v102, v102, v103
	v_cvt_pk_bf16_f32 v103, v104, v105
	v_cvt_pk_bf16_f32 v106, v106, v107
	v_cvt_pk_bf16_f32 v107, v108, v109
	v_cvt_pk_bf16_f32 v110, v110, v111
	v_cvt_pk_bf16_f32 v111, v112, v113
	v_cvt_pk_bf16_f32 v114, v114, v115
	v_cvt_pk_bf16_f32 v115, v116, v117
	global_store_dwordx2 v214, v[102:103], s[70:71] offset:0
	global_store_dwordx2 v214, v[106:107], s[70:71] offset:512
	global_store_dwordx2 v214, v[110:111], s[70:71] offset:1024
	global_store_dwordx2 v214, v[114:115], s[70:71] offset:1536
	s_waitcnt vmcnt(48)
	v_pk_add_f32 v[76:77], v[118:119], v[120:121]
	v_pk_add_f32 v[136:137], v[122:123], v[124:125]
	v_pk_add_f32 v[138:139], v[144:145], v[146:147]
	v_pk_add_f32 v[208:209], v[148:149], v[150:151]
	v_pk_add_f32 v[76:77], v[76:77], v[136:137]
	v_pk_add_f32 v[138:139], v[138:139], v[208:209]
	v_pk_add_f32 v[76:77], v[76:77], v[138:139]
	v_add_f32_e32 v131, v76, v77
	s_nop 1
	v_add_f32_dpp v131, v131, v131 quad_perm:[1,0,3,2] row_mask:0xf bank_mask:0xf bound_ctrl:1
	s_nop 1
	v_add_f32_dpp v131, v131, v131 quad_perm:[2,3,0,1] row_mask:0xf bank_mask:0xf bound_ctrl:1
	s_nop 1
	v_add_f32_dpp v131, v131, v131 row_half_mirror row_mask:0xf bank_mask:0xf bound_ctrl:1
	s_nop 1
	v_add_f32_dpp v131, v131, v131 row_mirror row_mask:0xf bank_mask:0xf bound_ctrl:1
	s_nop 1
	v_readlane_b32 s56, v131, 0
	v_readlane_b32 s57, v131, 16
	v_readlane_b32 s58, v131, 32
	v_readlane_b32 s59, v131, 48
	v_mov_b32_e32 v222, s57
	v_mov_b32_e32 v223, s59
	v_add_f32_e32 v222, s56, v222
	v_add_f32_e32 v223, s58, v223
	v_add_f32_e32 v131, v222, v223
	v_mul_f32_e32 v216, 0x3a800000, v131
	v_pk_add_f32 v[118:119], v[118:119], v[216:217] op_sel_hi:[1,0] neg_lo:[0,1] neg_hi:[0,1]
	v_pk_add_f32 v[120:121], v[120:121], v[216:217] op_sel_hi:[1,0] neg_lo:[0,1] neg_hi:[0,1]
	v_pk_add_f32 v[122:123], v[122:123], v[216:217] op_sel_hi:[1,0] neg_lo:[0,1] neg_hi:[0,1]
	v_pk_add_f32 v[124:125], v[124:125], v[216:217] op_sel_hi:[1,0] neg_lo:[0,1] neg_hi:[0,1]
	v_pk_add_f32 v[144:145], v[144:145], v[216:217] op_sel_hi:[1,0] neg_lo:[0,1] neg_hi:[0,1]
	v_pk_add_f32 v[146:147], v[146:147], v[216:217] op_sel_hi:[1,0] neg_lo:[0,1] neg_hi:[0,1]
	v_pk_add_f32 v[148:149], v[148:149], v[216:217] op_sel_hi:[1,0] neg_lo:[0,1] neg_hi:[0,1]
	v_pk_add_f32 v[150:151], v[150:151], v[216:217] op_sel_hi:[1,0] neg_lo:[0,1] neg_hi:[0,1]
	v_pk_mul_f32 v[76:77], v[118:119], v[118:119]
	v_pk_mul_f32 v[136:137], v[120:121], v[120:121]
	v_add_f32_e32 v133, v76, v77
	v_add_f32_e32 v133, v136, v133
	v_add_f32_e32 v133, v137, v133
	v_pk_mul_f32 v[76:77], v[122:123], v[122:123]
	v_pk_mul_f32 v[136:137], v[124:125], v[124:125]
	v_add_f32_e32 v133, v76, v133
	v_add_f32_e32 v133, v77, v133
	v_add_f32_e32 v133, v136, v133
	v_add_f32_e32 v133, v137, v133
	v_pk_mul_f32 v[76:77], v[144:145], v[144:145]
	v_pk_mul_f32 v[136:137], v[146:147], v[146:147]
	v_add_f32_e32 v133, v76, v133
	v_add_f32_e32 v133, v77, v133
	v_add_f32_e32 v133, v136, v133
	v_add_f32_e32 v133, v137, v133
	v_pk_mul_f32 v[76:77], v[148:149], v[148:149]
	v_pk_mul_f32 v[136:137], v[150:151], v[150:151]
	v_add_f32_e32 v133, v76, v133
	v_add_f32_e32 v133, v77, v133
	v_add_f32_e32 v133, v136, v133
	v_add_f32_e32 v133, v137, v133
	s_nop 1
	v_add_f32_dpp v133, v133, v133 quad_perm:[1,0,3,2] row_mask:0xf bank_mask:0xf bound_ctrl:1
	s_nop 1
	v_add_f32_dpp v133, v133, v133 quad_perm:[2,3,0,1] row_mask:0xf bank_mask:0xf bound_ctrl:1
	s_nop 1
	v_add_f32_dpp v133, v133, v133 row_half_mirror row_mask:0xf bank_mask:0xf bound_ctrl:1
	s_nop 1
	v_add_f32_dpp v133, v133, v133 row_mirror row_mask:0xf bank_mask:0xf bound_ctrl:1
	s_nop 1
	v_readlane_b32 s56, v133, 0
	v_readlane_b32 s57, v133, 16
	v_readlane_b32 s58, v133, 32
	v_readlane_b32 s59, v133, 48
	v_mov_b32_e32 v222, s57
	v_mov_b32_e32 v223, s59
	v_add_f32_e32 v222, s56, v222
	v_add_f32_e32 v223, s58, v223
	v_add_f32_e32 v133, v222, v223
	v_fmamk_f32 v133, v133, 0x3a800000, v215
	v_cmp_gt_f32_e32 vcc, s33, v133
	v_mul_f32_e32 v222, 0x4b800000, v133
	s_nop 0
	v_cndmask_b32_e32 v133, v133, v222, vcc
	v_rsq_f32_e32 v133, v133
	s_nop 0
	v_mul_f32_e32 v222, 0x45800000, v133
	v_cndmask_b32_e32 v220, v133, v222, vcc
	v_pk_mul_f32 v[118:119], v[118:119], v[220:221] op_sel_hi:[1,0]
	v_pk_mul_f32 v[120:121], v[120:121], v[220:221] op_sel_hi:[1,0]
	v_pk_mul_f32 v[122:123], v[122:123], v[220:221] op_sel_hi:[1,0]
	v_pk_mul_f32 v[124:125], v[124:125], v[220:221] op_sel_hi:[1,0]
	v_pk_mul_f32 v[144:145], v[144:145], v[220:221] op_sel_hi:[1,0]
	v_pk_mul_f32 v[146:147], v[146:147], v[220:221] op_sel_hi:[1,0]
	v_pk_mul_f32 v[148:149], v[148:149], v[220:221] op_sel_hi:[1,0]
	v_pk_mul_f32 v[150:151], v[150:151], v[220:221] op_sel_hi:[1,0]
	v_pk_fma_f32 v[118:119], v[184:185], v[118:119], v[200:201]
	v_pk_fma_f32 v[120:121], v[186:187], v[120:121], v[202:203]
	v_pk_fma_f32 v[122:123], v[188:189], v[122:123], v[204:205]
	v_pk_fma_f32 v[124:125], v[190:191], v[124:125], v[206:207]
	v_pk_fma_f32 v[144:145], v[192:193], v[144:145], v[226:227]
	v_pk_fma_f32 v[146:147], v[194:195], v[146:147], v[228:229]
	v_pk_fma_f32 v[148:149], v[196:197], v[148:149], v[230:231]
	v_pk_fma_f32 v[150:151], v[198:199], v[150:151], v[232:233]
	global_store_dwordx4 v212, v[118:121], s[52:53] offset:0
	global_store_dwordx4 v212, v[122:125], s[52:53] offset:1024
	global_store_dwordx4 v212, v[144:147], s[52:53] offset:2048
	global_store_dwordx4 v212, v[148:151], s[52:53] offset:3072
	v_cvt_pk_bf16_f32 v118, v118, v119
	v_cvt_pk_bf16_f32 v119, v120, v121
	v_cvt_pk_bf16_f32 v122, v122, v123
	v_cvt_pk_bf16_f32 v123, v124, v125
	v_cvt_pk_bf16_f32 v144, v144, v145
	v_cvt_pk_bf16_f32 v145, v146, v147
	v_cvt_pk_bf16_f32 v148, v148, v149
	v_cvt_pk_bf16_f32 v149, v150, v151
	global_store_dwordx2 v214, v[118:119], s[70:71] offset:2048
	global_store_dwordx2 v214, v[122:123], s[70:71] offset:2560
	global_store_dwordx2 v214, v[144:145], s[70:71] offset:3072
	global_store_dwordx2 v214, v[148:149], s[70:71] offset:3584
	s_waitcnt vmcnt(52)
	v_pk_add_f32 v[76:77], v[152:153], v[154:155]
	v_pk_add_f32 v[136:137], v[156:157], v[158:159]
	v_pk_add_f32 v[138:139], v[160:161], v[162:163]
	v_pk_add_f32 v[208:209], v[164:165], v[166:167]
	v_pk_add_f32 v[76:77], v[76:77], v[136:137]
	v_pk_add_f32 v[138:139], v[138:139], v[208:209]
	v_pk_add_f32 v[76:77], v[76:77], v[138:139]
	v_add_f32_e32 v131, v76, v77
	s_nop 1
	v_add_f32_dpp v131, v131, v131 quad_perm:[1,0,3,2] row_mask:0xf bank_mask:0xf bound_ctrl:1
	s_nop 1
	v_add_f32_dpp v131, v131, v131 quad_perm:[2,3,0,1] row_mask:0xf bank_mask:0xf bound_ctrl:1
	s_nop 1
	v_add_f32_dpp v131, v131, v131 row_half_mirror row_mask:0xf bank_mask:0xf bound_ctrl:1
	s_nop 1
	v_add_f32_dpp v131, v131, v131 row_mirror row_mask:0xf bank_mask:0xf bound_ctrl:1
	s_nop 1
	v_readlane_b32 s56, v131, 0
	v_readlane_b32 s57, v131, 16
	v_readlane_b32 s58, v131, 32
	v_readlane_b32 s59, v131, 48
	v_mov_b32_e32 v222, s57
	v_mov_b32_e32 v223, s59
	v_add_f32_e32 v222, s56, v222
	v_add_f32_e32 v223, s58, v223
	v_add_f32_e32 v131, v222, v223
	v_mul_f32_e32 v216, 0x3a800000, v131
	v_pk_add_f32 v[152:153], v[152:153], v[216:217] op_sel_hi:[1,0] neg_lo:[0,1] neg_hi:[0,1]
	v_pk_add_f32 v[154:155], v[154:155], v[216:217] op_sel_hi:[1,0] neg_lo:[0,1] neg_hi:[0,1]
	v_pk_add_f32 v[156:157], v[156:157], v[216:217] op_sel_hi:[1,0] neg_lo:[0,1] neg_hi:[0,1]
	v_pk_add_f32 v[158:159], v[158:159], v[216:217] op_sel_hi:[1,0] neg_lo:[0,1] neg_hi:[0,1]
	v_pk_add_f32 v[160:161], v[160:161], v[216:217] op_sel_hi:[1,0] neg_lo:[0,1] neg_hi:[0,1]
	v_pk_add_f32 v[162:163], v[162:163], v[216:217] op_sel_hi:[1,0] neg_lo:[0,1] neg_hi:[0,1]
	v_pk_add_f32 v[164:165], v[164:165], v[216:217] op_sel_hi:[1,0] neg_lo:[0,1] neg_hi:[0,1]
	v_pk_add_f32 v[166:167], v[166:167], v[216:217] op_sel_hi:[1,0] neg_lo:[0,1] neg_hi:[0,1]
	v_pk_mul_f32 v[76:77], v[152:153], v[152:153]
	v_pk_mul_f32 v[136:137], v[154:155], v[154:155]
	v_add_f32_e32 v133, v76, v77
	v_add_f32_e32 v133, v136, v133
	v_add_f32_e32 v133, v137, v133
	v_pk_mul_f32 v[76:77], v[156:157], v[156:157]
	v_pk_mul_f32 v[136:137], v[158:159], v[158:159]
	v_add_f32_e32 v133, v76, v133
	v_add_f32_e32 v133, v77, v133
	v_add_f32_e32 v133, v136, v133
	v_add_f32_e32 v133, v137, v133
	v_pk_mul_f32 v[76:77], v[160:161], v[160:161]
	v_pk_mul_f32 v[136:137], v[162:163], v[162:163]
	v_add_f32_e32 v133, v76, v133
	v_add_f32_e32 v133, v77, v133
	v_add_f32_e32 v133, v136, v133
	v_add_f32_e32 v133, v137, v133
	v_pk_mul_f32 v[76:77], v[164:165], v[164:165]
	v_pk_mul_f32 v[136:137], v[166:167], v[166:167]
	v_add_f32_e32 v133, v76, v133
	v_add_f32_e32 v133, v77, v133
	v_add_f32_e32 v133, v136, v133
	v_add_f32_e32 v133, v137, v133
	s_nop 1
	v_add_f32_dpp v133, v133, v133 quad_perm:[1,0,3,2] row_mask:0xf bank_mask:0xf bound_ctrl:1
	s_nop 1
	v_add_f32_dpp v133, v133, v133 quad_perm:[2,3,0,1] row_mask:0xf bank_mask:0xf bound_ctrl:1
	s_nop 1
	v_add_f32_dpp v133, v133, v133 row_half_mirror row_mask:0xf bank_mask:0xf bound_ctrl:1
	s_nop 1
	v_add_f32_dpp v133, v133, v133 row_mirror row_mask:0xf bank_mask:0xf bound_ctrl:1
	s_nop 1
	v_readlane_b32 s56, v133, 0
	v_readlane_b32 s57, v133, 16
	v_readlane_b32 s58, v133, 32
	v_readlane_b32 s59, v133, 48
	v_mov_b32_e32 v222, s57
	v_mov_b32_e32 v223, s59
	v_add_f32_e32 v222, s56, v222
	v_add_f32_e32 v223, s58, v223
	v_add_f32_e32 v133, v222, v223
	v_fmamk_f32 v133, v133, 0x3a800000, v215
	v_cmp_gt_f32_e32 vcc, s33, v133
	v_mul_f32_e32 v222, 0x4b800000, v133
	s_nop 0
	v_cndmask_b32_e32 v133, v133, v222, vcc
	v_rsq_f32_e32 v133, v133
	s_nop 0
	v_mul_f32_e32 v222, 0x45800000, v133
	v_cndmask_b32_e32 v220, v133, v222, vcc
	v_pk_mul_f32 v[152:153], v[152:153], v[220:221] op_sel_hi:[1,0]
	v_pk_mul_f32 v[154:155], v[154:155], v[220:221] op_sel_hi:[1,0]
	v_pk_mul_f32 v[156:157], v[156:157], v[220:221] op_sel_hi:[1,0]
	v_pk_mul_f32 v[158:159], v[158:159], v[220:221] op_sel_hi:[1,0]
	v_pk_mul_f32 v[160:161], v[160:161], v[220:221] op_sel_hi:[1,0]
	v_pk_mul_f32 v[162:163], v[162:163], v[220:221] op_sel_hi:[1,0]
	v_pk_mul_f32 v[164:165], v[164:165], v[220:221] op_sel_hi:[1,0]
	v_pk_mul_f32 v[166:167], v[166:167], v[220:221] op_sel_hi:[1,0]
	v_pk_fma_f32 v[152:153], v[184:185], v[152:153], v[200:201]
	v_pk_fma_f32 v[154:155], v[186:187], v[154:155], v[202:203]
	v_pk_fma_f32 v[156:157], v[188:189], v[156:157], v[204:205]
	v_pk_fma_f32 v[158:159], v[190:191], v[158:159], v[206:207]
	v_pk_fma_f32 v[160:161], v[192:193], v[160:161], v[226:227]
	v_pk_fma_f32 v[162:163], v[194:195], v[162:163], v[228:229]
	v_pk_fma_f32 v[164:165], v[196:197], v[164:165], v[230:231]
	v_pk_fma_f32 v[166:167], v[198:199], v[166:167], v[232:233]
	global_store_dwordx4 v212, v[152:155], s[62:63] offset:0
	global_store_dwordx4 v212, v[156:159], s[62:63] offset:1024
	global_store_dwordx4 v212, v[160:163], s[62:63] offset:2048
	global_store_dwordx4 v212, v[164:167], s[62:63] offset:3072
	v_cvt_pk_bf16_f32 v152, v152, v153
	v_cvt_pk_bf16_f32 v153, v154, v155
	v_cvt_pk_bf16_f32 v156, v156, v157
	v_cvt_pk_bf16_f32 v157, v158, v159
	v_cvt_pk_bf16_f32 v160, v160, v161
	v_cvt_pk_bf16_f32 v161, v162, v163
	v_cvt_pk_bf16_f32 v164, v164, v165
	v_cvt_pk_bf16_f32 v165, v166, v167
	global_store_dwordx2 v214, v[152:153], s[72:73] offset:0
	global_store_dwordx2 v214, v[156:157], s[72:73] offset:512
	global_store_dwordx2 v214, v[160:161], s[72:73] offset:1024
	global_store_dwordx2 v214, v[164:165], s[72:73] offset:1536
	s_waitcnt vmcnt(56)
	v_pk_add_f32 v[76:77], v[168:169], v[170:171]
	v_pk_add_f32 v[136:137], v[172:173], v[174:175]
	v_pk_add_f32 v[138:139], v[176:177], v[178:179]
	v_pk_add_f32 v[208:209], v[180:181], v[182:183]
	v_pk_add_f32 v[76:77], v[76:77], v[136:137]
	v_pk_add_f32 v[138:139], v[138:139], v[208:209]
	v_pk_add_f32 v[76:77], v[76:77], v[138:139]
	v_add_f32_e32 v131, v76, v77
	s_nop 1
	v_add_f32_dpp v131, v131, v131 quad_perm:[1,0,3,2] row_mask:0xf bank_mask:0xf bound_ctrl:1
	s_nop 1
	v_add_f32_dpp v131, v131, v131 quad_perm:[2,3,0,1] row_mask:0xf bank_mask:0xf bound_ctrl:1
	s_nop 1
	v_add_f32_dpp v131, v131, v131 row_half_mirror row_mask:0xf bank_mask:0xf bound_ctrl:1
	s_nop 1
	v_add_f32_dpp v131, v131, v131 row_mirror row_mask:0xf bank_mask:0xf bound_ctrl:1
	s_nop 1
	v_readlane_b32 s56, v131, 0
	v_readlane_b32 s57, v131, 16
	v_readlane_b32 s58, v131, 32
	v_readlane_b32 s59, v131, 48
	v_mov_b32_e32 v222, s57
	v_mov_b32_e32 v223, s59
	v_add_f32_e32 v222, s56, v222
	v_add_f32_e32 v223, s58, v223
	v_add_f32_e32 v131, v222, v223
	v_mul_f32_e32 v216, 0x3a800000, v131
	v_pk_add_f32 v[168:169], v[168:169], v[216:217] op_sel_hi:[1,0] neg_lo:[0,1] neg_hi:[0,1]
	v_pk_add_f32 v[170:171], v[170:171], v[216:217] op_sel_hi:[1,0] neg_lo:[0,1] neg_hi:[0,1]
	v_pk_add_f32 v[172:173], v[172:173], v[216:217] op_sel_hi:[1,0] neg_lo:[0,1] neg_hi:[0,1]
	v_pk_add_f32 v[174:175], v[174:175], v[216:217] op_sel_hi:[1,0] neg_lo:[0,1] neg_hi:[0,1]
	v_pk_add_f32 v[176:177], v[176:177], v[216:217] op_sel_hi:[1,0] neg_lo:[0,1] neg_hi:[0,1]
	v_pk_add_f32 v[178:179], v[178:179], v[216:217] op_sel_hi:[1,0] neg_lo:[0,1] neg_hi:[0,1]
	v_pk_add_f32 v[180:181], v[180:181], v[216:217] op_sel_hi:[1,0] neg_lo:[0,1] neg_hi:[0,1]
	v_pk_add_f32 v[182:183], v[182:183], v[216:217] op_sel_hi:[1,0] neg_lo:[0,1] neg_hi:[0,1]
	v_pk_mul_f32 v[76:77], v[168:169], v[168:169]
	v_pk_mul_f32 v[136:137], v[170:171], v[170:171]
	v_add_f32_e32 v133, v76, v77
	v_add_f32_e32 v133, v136, v133
	v_add_f32_e32 v133, v137, v133
	v_pk_mul_f32 v[76:77], v[172:173], v[172:173]
	v_pk_mul_f32 v[136:137], v[174:175], v[174:175]
	v_add_f32_e32 v133, v76, v133
	v_add_f32_e32 v133, v77, v133
	v_add_f32_e32 v133, v136, v133
	v_add_f32_e32 v133, v137, v133
	v_pk_mul_f32 v[76:77], v[176:177], v[176:177]
	v_pk_mul_f32 v[136:137], v[178:179], v[178:179]
	v_add_f32_e32 v133, v76, v133
	v_add_f32_e32 v133, v77, v133
	v_add_f32_e32 v133, v136, v133
	v_add_f32_e32 v133, v137, v133
	v_pk_mul_f32 v[76:77], v[180:181], v[180:181]
	v_pk_mul_f32 v[136:137], v[182:183], v[182:183]
	v_add_f32_e32 v133, v76, v133
	v_add_f32_e32 v133, v77, v133
	v_add_f32_e32 v133, v136, v133
	v_add_f32_e32 v133, v137, v133
	s_nop 1
	v_add_f32_dpp v133, v133, v133 quad_perm:[1,0,3,2] row_mask:0xf bank_mask:0xf bound_ctrl:1
	s_nop 1
	v_add_f32_dpp v133, v133, v133 quad_perm:[2,3,0,1] row_mask:0xf bank_mask:0xf bound_ctrl:1
	s_nop 1
	v_add_f32_dpp v133, v133, v133 row_half_mirror row_mask:0xf bank_mask:0xf bound_ctrl:1
	s_nop 1
	v_add_f32_dpp v133, v133, v133 row_mirror row_mask:0xf bank_mask:0xf bound_ctrl:1
	s_nop 1
	v_readlane_b32 s56, v133, 0
	v_readlane_b32 s57, v133, 16
	v_readlane_b32 s58, v133, 32
	v_readlane_b32 s59, v133, 48
	v_mov_b32_e32 v222, s57
	v_mov_b32_e32 v223, s59
	v_add_f32_e32 v222, s56, v222
	v_add_f32_e32 v223, s58, v223
	v_add_f32_e32 v133, v222, v223
	v_fmamk_f32 v133, v133, 0x3a800000, v215
	v_cmp_gt_f32_e32 vcc, s33, v133
	v_mul_f32_e32 v222, 0x4b800000, v133
	s_nop 0
	v_cndmask_b32_e32 v133, v133, v222, vcc
	v_rsq_f32_e32 v133, v133
	s_nop 0
	v_mul_f32_e32 v222, 0x45800000, v133
	v_cndmask_b32_e32 v220, v133, v222, vcc
	v_pk_mul_f32 v[168:169], v[168:169], v[220:221] op_sel_hi:[1,0]
	v_pk_mul_f32 v[170:171], v[170:171], v[220:221] op_sel_hi:[1,0]
	v_pk_mul_f32 v[172:173], v[172:173], v[220:221] op_sel_hi:[1,0]
	v_pk_mul_f32 v[174:175], v[174:175], v[220:221] op_sel_hi:[1,0]
	v_pk_mul_f32 v[176:177], v[176:177], v[220:221] op_sel_hi:[1,0]
	v_pk_mul_f32 v[178:179], v[178:179], v[220:221] op_sel_hi:[1,0]
	v_pk_mul_f32 v[180:181], v[180:181], v[220:221] op_sel_hi:[1,0]
	v_pk_mul_f32 v[182:183], v[182:183], v[220:221] op_sel_hi:[1,0]
	v_pk_fma_f32 v[168:169], v[184:185], v[168:169], v[200:201]
	v_pk_fma_f32 v[170:171], v[186:187], v[170:171], v[202:203]
	v_pk_fma_f32 v[172:173], v[188:189], v[172:173], v[204:205]
	v_pk_fma_f32 v[174:175], v[190:191], v[174:175], v[206:207]
	v_pk_fma_f32 v[176:177], v[192:193], v[176:177], v[226:227]
	v_pk_fma_f32 v[178:179], v[194:195], v[178:179], v[228:229]
	v_pk_fma_f32 v[180:181], v[196:197], v[180:181], v[230:231]
	v_pk_fma_f32 v[182:183], v[198:199], v[182:183], v[232:233]
	global_store_dwordx4 v212, v[168:171], s[64:65] offset:0
	global_store_dwordx4 v212, v[172:175], s[64:65] offset:1024
	global_store_dwordx4 v212, v[176:179], s[64:65] offset:2048
	global_store_dwordx4 v212, v[180:183], s[64:65] offset:3072
	v_cvt_pk_bf16_f32 v168, v168, v169
	v_cvt_pk_bf16_f32 v169, v170, v171
	v_cvt_pk_bf16_f32 v172, v172, v173
	v_cvt_pk_bf16_f32 v173, v174, v175
	v_cvt_pk_bf16_f32 v176, v176, v177
	v_cvt_pk_bf16_f32 v177, v178, v179
	v_cvt_pk_bf16_f32 v180, v180, v181
	v_cvt_pk_bf16_f32 v181, v182, v183
	global_store_dwordx2 v214, v[168:169], s[72:73] offset:2048
	global_store_dwordx2 v214, v[172:173], s[72:73] offset:2560
	global_store_dwordx2 v214, v[176:177], s[72:73] offset:3072
	global_store_dwordx2 v214, v[180:181], s[72:73] offset:3584
	s_xor_b64 s[22:23], exec, -1
	s_branch .LBB0_55

.LBB0_1618:
	v_lshlrev_b32_e32 v212, 4, v219
	v_lshlrev_b32_e32 v214, 3, v219
	v_readfirstlane_b32 s42, v32
	v_readfirstlane_b32 s43, v33
	v_readfirstlane_b32 s66, v30
	v_readfirstlane_b32 s67, v31
	global_load_dwordx4 v[184:187], v[26:27], off offset:0
	global_load_dwordx4 v[188:191], v[26:27], off offset:1024
	global_load_dwordx4 v[192:195], v[26:27], off offset:2048
	global_load_dwordx4 v[196:199], v[26:27], off offset:3072
	global_load_dwordx4 v[200:203], v[28:29], off offset:0
	global_load_dwordx4 v[204:207], v[28:29], off offset:1024
	global_load_dwordx4 v[226:229], v[28:29], off offset:2048
	global_load_dwordx4 v[230:233], v[28:29], off offset:3072
	s_sub_u32 s42, s42, 0x1000
	s_subb_u32 s43, s43, 0
	global_load_dwordx4 v[2:5], v212, s[42:43] offset:0
	global_load_dwordx4 v[6:9], v212, s[42:43] offset:1024
	global_load_dwordx4 v[10:13], v212, s[42:43] offset:2048
	global_load_dwordx4 v[14:17], v212, s[42:43] offset:3072
	s_add_u32 s44, s42, 0x1000
	s_addc_u32 s45, s43, 0
	global_load_dwordx4 v[18:21], v212, s[44:45] offset:0
	global_load_dwordx4 v[22:25], v212, s[44:45] offset:1024
	global_load_dwordx4 v[34:37], v212, s[44:45] offset:2048
	global_load_dwordx4 v[38:41], v212, s[44:45] offset:3072
	s_add_u32 s46, s44, 0x1000
	s_addc_u32 s47, s45, 0
	global_load_dwordx4 v[44:47], v212, s[46:47] offset:0
	global_load_dwordx4 v[48:51], v212, s[46:47] offset:1024
	global_load_dwordx4 v[52:55], v212, s[46:47] offset:2048
	global_load_dwordx4 v[56:59], v212, s[46:47] offset:3072
	s_add_u32 s48, s46, 0x1000
	s_addc_u32 s49, s47, 0
	global_load_dwordx4 v[60:63], v212, s[48:49] offset:0
	global_load_dwordx4 v[64:67], v212, s[48:49] offset:1024
	global_load_dwordx4 v[94:97], v212, s[48:49] offset:2048
	global_load_dwordx4 v[98:101], v212, s[48:49] offset:3072
	s_add_u32 s50, s48, 0x1000
	s_addc_u32 s51, s49, 0
	global_load_dwordx4 v[102:105], v212, s[50:51] offset:0
	global_load_dwordx4 v[106:109], v212, s[50:51] offset:1024
	global_load_dwordx4 v[110:113], v212, s[50:51] offset:2048
	global_load_dwordx4 v[114:117], v212, s[50:51] offset:3072
	s_add_u32 s52, s50, 0x1000
	s_addc_u32 s53, s51, 0
	global_load_dwordx4 v[118:121], v212, s[52:53] offset:0
	global_load_dwordx4 v[122:125], v212, s[52:53] offset:1024
	global_load_dwordx4 v[144:147], v212, s[52:53] offset:2048
	global_load_dwordx4 v[148:151], v212, s[52:53] offset:3072
	s_add_u32 s62, s52, 0x1000
	s_addc_u32 s63, s53, 0
	global_load_dwordx4 v[152:155], v212, s[62:63] offset:0
	global_load_dwordx4 v[156:159], v212, s[62:63] offset:1024
	global_load_dwordx4 v[160:163], v212, s[62:63] offset:2048
	global_load_dwordx4 v[164:167], v212, s[62:63] offset:3072
	s_add_u32 s64, s62, 0x1000
	s_addc_u32 s65, s63, 0
	global_load_dwordx4 v[168:171], v212, s[64:65] offset:0
	global_load_dwordx4 v[172:175], v212, s[64:65] offset:1024
	global_load_dwordx4 v[176:179], v212, s[64:65] offset:2048
	global_load_dwordx4 v[180:183], v212, s[64:65] offset:3072
	s_add_u32 s66, s66, 0x1f80000
	s_addc_u32 s67, s67, 0
	s_add_u32 s68, s66, 0x1000
	s_addc_u32 s69, s67, 0
	s_add_u32 s70, s68, 0x1000
	s_addc_u32 s71, s69, 0
	s_add_u32 s72, s70, 0x1000
	s_addc_u32 s73, s71, 0
	s_waitcnt vmcnt(28)
	v_pk_add_f32 v[76:77], v[2:3], v[4:5]
	v_pk_add_f32 v[136:137], v[6:7], v[8:9]
	v_pk_add_f32 v[138:139], v[10:11], v[12:13]
	v_pk_add_f32 v[208:209], v[14:15], v[16:17]
	v_pk_add_f32 v[76:77], v[76:77], v[136:137]
	v_pk_add_f32 v[138:139], v[138:139], v[208:209]
	v_pk_add_f32 v[76:77], v[76:77], v[138:139]
	v_add_f32_e32 v131, v76, v77
	s_nop 1
	v_add_f32_dpp v131, v131, v131 quad_perm:[1,0,3,2] row_mask:0xf bank_mask:0xf bound_ctrl:1
	s_nop 1
	v_add_f32_dpp v131, v131, v131 quad_perm:[2,3,0,1] row_mask:0xf bank_mask:0xf bound_ctrl:1
	s_nop 1
	v_add_f32_dpp v131, v131, v131 row_half_mirror row_mask:0xf bank_mask:0xf bound_ctrl:1
	s_nop 1
	v_add_f32_dpp v131, v131, v131 row_mirror row_mask:0xf bank_mask:0xf bound_ctrl:1
	s_nop 1
	v_readlane_b32 s56, v131, 0
	v_readlane_b32 s57, v131, 16
	v_readlane_b32 s58, v131, 32
	v_readlane_b32 s59, v131, 48
	v_mov_b32_e32 v222, s57
	v_mov_b32_e32 v223, s59
	v_add_f32_e32 v222, s56, v222
	v_add_f32_e32 v223, s58, v223
	v_add_f32_e32 v131, v222, v223
	v_mul_f32_e32 v216, 0x3a800000, v131
	v_pk_add_f32 v[2:3], v[2:3], v[216:217] op_sel_hi:[1,0] neg_lo:[0,1] neg_hi:[0,1]
	v_pk_add_f32 v[4:5], v[4:5], v[216:217] op_sel_hi:[1,0] neg_lo:[0,1] neg_hi:[0,1]
	v_pk_add_f32 v[6:7], v[6:7], v[216:217] op_sel_hi:[1,0] neg_lo:[0,1] neg_hi:[0,1]
	v_pk_add_f32 v[8:9], v[8:9], v[216:217] op_sel_hi:[1,0] neg_lo:[0,1] neg_hi:[0,1]
	v_pk_add_f32 v[10:11], v[10:11], v[216:217] op_sel_hi:[1,0] neg_lo:[0,1] neg_hi:[0,1]
	v_pk_add_f32 v[12:13], v[12:13], v[216:217] op_sel_hi:[1,0] neg_lo:[0,1] neg_hi:[0,1]
	v_pk_add_f32 v[14:15], v[14:15], v[216:217] op_sel_hi:[1,0] neg_lo:[0,1] neg_hi:[0,1]
	v_pk_add_f32 v[16:17], v[16:17], v[216:217] op_sel_hi:[1,0] neg_lo:[0,1] neg_hi:[0,1]
	v_pk_mul_f32 v[76:77], v[2:3], v[2:3]
	v_pk_mul_f32 v[136:137], v[4:5], v[4:5]
	v_add_f32_e32 v133, v76, v77
	v_add_f32_e32 v133, v136, v133
	v_add_f32_e32 v133, v137, v133
	v_pk_mul_f32 v[76:77], v[6:7], v[6:7]
	v_pk_mul_f32 v[136:137], v[8:9], v[8:9]
	v_add_f32_e32 v133, v76, v133
	v_add_f32_e32 v133, v77, v133
	v_add_f32_e32 v133, v136, v133
	v_add_f32_e32 v133, v137, v133
	v_pk_mul_f32 v[76:77], v[10:11], v[10:11]
	v_pk_mul_f32 v[136:137], v[12:13], v[12:13]
	v_add_f32_e32 v133, v76, v133
	v_add_f32_e32 v133, v77, v133
	v_add_f32_e32 v133, v136, v133
	v_add_f32_e32 v133, v137, v133
	v_pk_mul_f32 v[76:77], v[14:15], v[14:15]
	v_pk_mul_f32 v[136:137], v[16:17], v[16:17]
	v_add_f32_e32 v133, v76, v133
	v_add_f32_e32 v133, v77, v133
	v_add_f32_e32 v133, v136, v133
	v_add_f32_e32 v133, v137, v133
	s_nop 1
	v_add_f32_dpp v133, v133, v133 quad_perm:[1,0,3,2] row_mask:0xf bank_mask:0xf bound_ctrl:1
	s_nop 1
	v_add_f32_dpp v133, v133, v133 quad_perm:[2,3,0,1] row_mask:0xf bank_mask:0xf bound_ctrl:1
	s_nop 1
	v_add_f32_dpp v133, v133, v133 row_half_mirror row_mask:0xf bank_mask:0xf bound_ctrl:1
	s_nop 1
	v_add_f32_dpp v133, v133, v133 row_mirror row_mask:0xf bank_mask:0xf bound_ctrl:1
	s_nop 1
	v_readlane_b32 s56, v133, 0
	v_readlane_b32 s57, v133, 16
	v_readlane_b32 s58, v133, 32
	v_readlane_b32 s59, v133, 48
	v_mov_b32_e32 v222, s57
	v_mov_b32_e32 v223, s59
	v_add_f32_e32 v222, s56, v222
	v_add_f32_e32 v223, s58, v223
	v_add_f32_e32 v133, v222, v223
	v_fmamk_f32 v133, v133, 0x3a800000, v215
	v_cmp_gt_f32_e32 vcc, s33, v133
	v_mul_f32_e32 v222, 0x4b800000, v133
	s_nop 0
	v_cndmask_b32_e32 v133, v133, v222, vcc
	v_rsq_f32_e32 v133, v133
	s_nop 0
	v_mul_f32_e32 v222, 0x45800000, v133
	v_cndmask_b32_e32 v220, v133, v222, vcc
	v_pk_mul_f32 v[2:3], v[2:3], v[220:221] op_sel_hi:[1,0]
	v_pk_mul_f32 v[4:5], v[4:5], v[220:221] op_sel_hi:[1,0]
	v_pk_mul_f32 v[6:7], v[6:7], v[220:221] op_sel_hi:[1,0]
	v_pk_mul_f32 v[8:9], v[8:9], v[220:221] op_sel_hi:[1,0]
	v_pk_mul_f32 v[10:11], v[10:11], v[220:221] op_sel_hi:[1,0]
	v_pk_mul_f32 v[12:13], v[12:13], v[220:221] op_sel_hi:[1,0]
	v_pk_mul_f32 v[14:15], v[14:15], v[220:221] op_sel_hi:[1,0]
	v_pk_mul_f32 v[16:17], v[16:17], v[220:221] op_sel_hi:[1,0]
	v_pk_fma_f32 v[2:3], v[184:185], v[2:3], v[200:201]
	v_pk_fma_f32 v[4:5], v[186:187], v[4:5], v[202:203]
	v_pk_fma_f32 v[6:7], v[188:189], v[6:7], v[204:205]
	v_pk_fma_f32 v[8:9], v[190:191], v[8:9], v[206:207]
	v_pk_fma_f32 v[10:11], v[192:193], v[10:11], v[226:227]
	v_pk_fma_f32 v[12:13], v[194:195], v[12:13], v[228:229]
	v_pk_fma_f32 v[14:15], v[196:197], v[14:15], v[230:231]
	v_pk_fma_f32 v[16:17], v[198:199], v[16:17], v[232:233]
	global_store_dwordx4 v212, v[2:5], s[42:43] offset:0
	global_store_dwordx4 v212, v[6:9], s[42:43] offset:1024
	global_store_dwordx4 v212, v[10:13], s[42:43] offset:2048
	global_store_dwordx4 v212, v[14:17], s[42:43] offset:3072
	v_cvt_pk_bf16_f32 v2, v2, v3
	v_cvt_pk_bf16_f32 v3, v4, v5
	v_cvt_pk_bf16_f32 v6, v6, v7
	v_cvt_pk_bf16_f32 v7, v8, v9
	v_cvt_pk_bf16_f32 v10, v10, v11
	v_cvt_pk_bf16_f32 v11, v12, v13
	v_cvt_pk_bf16_f32 v14, v14, v15
	v_cvt_pk_bf16_f32 v15, v16, v17
	global_store_dwordx2 v214, v[2:3], s[66:67] offset:0
	global_store_dwordx2 v214, v[6:7], s[66:67] offset:512
	global_store_dwordx2 v214, v[10:11], s[66:67] offset:1024
	global_store_dwordx2 v214, v[14:15], s[66:67] offset:1536
	s_waitcnt vmcnt(32)
	v_pk_add_f32 v[76:77], v[18:19], v[20:21]
	v_pk_add_f32 v[136:137], v[22:23], v[24:25]
	v_pk_add_f32 v[138:139], v[34:35], v[36:37]
	v_pk_add_f32 v[208:209], v[38:39], v[40:41]
	v_pk_add_f32 v[76:77], v[76:77], v[136:137]
	v_pk_add_f32 v[138:139], v[138:139], v[208:209]
	v_pk_add_f32 v[76:77], v[76:77], v[138:139]
	v_add_f32_e32 v131, v76, v77
	s_nop 1
	v_add_f32_dpp v131, v131, v131 quad_perm:[1,0,3,2] row_mask:0xf bank_mask:0xf bound_ctrl:1
	s_nop 1
	v_add_f32_dpp v131, v131, v131 quad_perm:[2,3,0,1] row_mask:0xf bank_mask:0xf bound_ctrl:1
	s_nop 1
	v_add_f32_dpp v131, v131, v131 row_half_mirror row_mask:0xf bank_mask:0xf bound_ctrl:1
	s_nop 1
	v_add_f32_dpp v131, v131, v131 row_mirror row_mask:0xf bank_mask:0xf bound_ctrl:1
	s_nop 1
	v_readlane_b32 s56, v131, 0
	v_readlane_b32 s57, v131, 16
	v_readlane_b32 s58, v131, 32
	v_readlane_b32 s59, v131, 48
	v_mov_b32_e32 v222, s57
	v_mov_b32_e32 v223, s59
	v_add_f32_e32 v222, s56, v222
	v_add_f32_e32 v223, s58, v223
	v_add_f32_e32 v131, v222, v223
	v_mul_f32_e32 v216, 0x3a800000, v131
	v_pk_add_f32 v[18:19], v[18:19], v[216:217] op_sel_hi:[1,0] neg_lo:[0,1] neg_hi:[0,1]
	v_pk_add_f32 v[20:21], v[20:21], v[216:217] op_sel_hi:[1,0] neg_lo:[0,1] neg_hi:[0,1]
	v_pk_add_f32 v[22:23], v[22:23], v[216:217] op_sel_hi:[1,0] neg_lo:[0,1] neg_hi:[0,1]
	v_pk_add_f32 v[24:25], v[24:25], v[216:217] op_sel_hi:[1,0] neg_lo:[0,1] neg_hi:[0,1]
	v_pk_add_f32 v[34:35], v[34:35], v[216:217] op_sel_hi:[1,0] neg_lo:[0,1] neg_hi:[0,1]
	v_pk_add_f32 v[36:37], v[36:37], v[216:217] op_sel_hi:[1,0] neg_lo:[0,1] neg_hi:[0,1]
	v_pk_add_f32 v[38:39], v[38:39], v[216:217] op_sel_hi:[1,0] neg_lo:[0,1] neg_hi:[0,1]
	v_pk_add_f32 v[40:41], v[40:41], v[216:217] op_sel_hi:[1,0] neg_lo:[0,1] neg_hi:[0,1]
	v_pk_mul_f32 v[76:77], v[18:19], v[18:19]
	v_pk_mul_f32 v[136:137], v[20:21], v[20:21]
	v_add_f32_e32 v133, v76, v77
	v_add_f32_e32 v133, v136, v133
	v_add_f32_e32 v133, v137, v133
	v_pk_mul_f32 v[76:77], v[22:23], v[22:23]
	v_pk_mul_f32 v[136:137], v[24:25], v[24:25]
	v_add_f32_e32 v133, v76, v133
	v_add_f32_e32 v133, v77, v133
	v_add_f32_e32 v133, v136, v133
	v_add_f32_e32 v133, v137, v133
	v_pk_mul_f32 v[76:77], v[34:35], v[34:35]
	v_pk_mul_f32 v[136:137], v[36:37], v[36:37]
	v_add_f32_e32 v133, v76, v133
	v_add_f32_e32 v133, v77, v133
	v_add_f32_e32 v133, v136, v133
	v_add_f32_e32 v133, v137, v133
	v_pk_mul_f32 v[76:77], v[38:39], v[38:39]
	v_pk_mul_f32 v[136:137], v[40:41], v[40:41]
	v_add_f32_e32 v133, v76, v133
	v_add_f32_e32 v133, v77, v133
	v_add_f32_e32 v133, v136, v133
	v_add_f32_e32 v133, v137, v133
	s_nop 1
	v_add_f32_dpp v133, v133, v133 quad_perm:[1,0,3,2] row_mask:0xf bank_mask:0xf bound_ctrl:1
	s_nop 1
	v_add_f32_dpp v133, v133, v133 quad_perm:[2,3,0,1] row_mask:0xf bank_mask:0xf bound_ctrl:1
	s_nop 1
	v_add_f32_dpp v133, v133, v133 row_half_mirror row_mask:0xf bank_mask:0xf bound_ctrl:1
	s_nop 1
	v_add_f32_dpp v133, v133, v133 row_mirror row_mask:0xf bank_mask:0xf bound_ctrl:1
	s_nop 1
	v_readlane_b32 s56, v133, 0
	v_readlane_b32 s57, v133, 16
	v_readlane_b32 s58, v133, 32
	v_readlane_b32 s59, v133, 48
	v_mov_b32_e32 v222, s57
	v_mov_b32_e32 v223, s59
	v_add_f32_e32 v222, s56, v222
	v_add_f32_e32 v223, s58, v223
	v_add_f32_e32 v133, v222, v223
	v_fmamk_f32 v133, v133, 0x3a800000, v215
	v_cmp_gt_f32_e32 vcc, s33, v133
	v_mul_f32_e32 v222, 0x4b800000, v133
	s_nop 0
	v_cndmask_b32_e32 v133, v133, v222, vcc
	v_rsq_f32_e32 v133, v133
	s_nop 0
	v_mul_f32_e32 v222, 0x45800000, v133
	v_cndmask_b32_e32 v220, v133, v222, vcc
	v_pk_mul_f32 v[18:19], v[18:19], v[220:221] op_sel_hi:[1,0]
	v_pk_mul_f32 v[20:21], v[20:21], v[220:221] op_sel_hi:[1,0]
	v_pk_mul_f32 v[22:23], v[22:23], v[220:221] op_sel_hi:[1,0]
	v_pk_mul_f32 v[24:25], v[24:25], v[220:221] op_sel_hi:[1,0]
	v_pk_mul_f32 v[34:35], v[34:35], v[220:221] op_sel_hi:[1,0]
	v_pk_mul_f32 v[36:37], v[36:37], v[220:221] op_sel_hi:[1,0]
	v_pk_mul_f32 v[38:39], v[38:39], v[220:221] op_sel_hi:[1,0]
	v_pk_mul_f32 v[40:41], v[40:41], v[220:221] op_sel_hi:[1,0]
	v_pk_fma_f32 v[18:19], v[184:185], v[18:19], v[200:201]
	v_pk_fma_f32 v[20:21], v[186:187], v[20:21], v[202:203]
	v_pk_fma_f32 v[22:23], v[188:189], v[22:23], v[204:205]
	v_pk_fma_f32 v[24:25], v[190:191], v[24:25], v[206:207]
	v_pk_fma_f32 v[34:35], v[192:193], v[34:35], v[226:227]
	v_pk_fma_f32 v[36:37], v[194:195], v[36:37], v[228:229]
	v_pk_fma_f32 v[38:39], v[196:197], v[38:39], v[230:231]
	v_pk_fma_f32 v[40:41], v[198:199], v[40:41], v[232:233]
	global_store_dwordx4 v212, v[18:21], s[44:45] offset:0
	global_store_dwordx4 v212, v[22:25], s[44:45] offset:1024
	global_store_dwordx4 v212, v[34:37], s[44:45] offset:2048
	global_store_dwordx4 v212, v[38:41], s[44:45] offset:3072
	v_cvt_pk_bf16_f32 v18, v18, v19
	v_cvt_pk_bf16_f32 v19, v20, v21
	v_cvt_pk_bf16_f32 v22, v22, v23
	v_cvt_pk_bf16_f32 v23, v24, v25
	v_cvt_pk_bf16_f32 v34, v34, v35
	v_cvt_pk_bf16_f32 v35, v36, v37
	v_cvt_pk_bf16_f32 v38, v38, v39
	v_cvt_pk_bf16_f32 v39, v40, v41
	global_store_dwordx2 v214, v[18:19], s[66:67] offset:2048
	global_store_dwordx2 v214, v[22:23], s[66:67] offset:2560
	global_store_dwordx2 v214, v[34:35], s[66:67] offset:3072
	global_store_dwordx2 v214, v[38:39], s[66:67] offset:3584
	s_waitcnt vmcnt(36)
	v_pk_add_f32 v[76:77], v[44:45], v[46:47]
	v_pk_add_f32 v[136:137], v[48:49], v[50:51]
	v_pk_add_f32 v[138:139], v[52:53], v[54:55]
	v_pk_add_f32 v[208:209], v[56:57], v[58:59]
	v_pk_add_f32 v[76:77], v[76:77], v[136:137]
	v_pk_add_f32 v[138:139], v[138:139], v[208:209]
	v_pk_add_f32 v[76:77], v[76:77], v[138:139]
	v_add_f32_e32 v131, v76, v77
	s_nop 1
	v_add_f32_dpp v131, v131, v131 quad_perm:[1,0,3,2] row_mask:0xf bank_mask:0xf bound_ctrl:1
	s_nop 1
	v_add_f32_dpp v131, v131, v131 quad_perm:[2,3,0,1] row_mask:0xf bank_mask:0xf bound_ctrl:1
	s_nop 1
	v_add_f32_dpp v131, v131, v131 row_half_mirror row_mask:0xf bank_mask:0xf bound_ctrl:1
	s_nop 1
	v_add_f32_dpp v131, v131, v131 row_mirror row_mask:0xf bank_mask:0xf bound_ctrl:1
	s_nop 1
	v_readlane_b32 s56, v131, 0
	v_readlane_b32 s57, v131, 16
	v_readlane_b32 s58, v131, 32
	v_readlane_b32 s59, v131, 48
	v_mov_b32_e32 v222, s57
	v_mov_b32_e32 v223, s59
	v_add_f32_e32 v222, s56, v222
	v_add_f32_e32 v223, s58, v223
	v_add_f32_e32 v131, v222, v223
	v_mul_f32_e32 v216, 0x3a800000, v131
	v_pk_add_f32 v[44:45], v[44:45], v[216:217] op_sel_hi:[1,0] neg_lo:[0,1] neg_hi:[0,1]
	v_pk_add_f32 v[46:47], v[46:47], v[216:217] op_sel_hi:[1,0] neg_lo:[0,1] neg_hi:[0,1]
	v_pk_add_f32 v[48:49], v[48:49], v[216:217] op_sel_hi:[1,0] neg_lo:[0,1] neg_hi:[0,1]
	v_pk_add_f32 v[50:51], v[50:51], v[216:217] op_sel_hi:[1,0] neg_lo:[0,1] neg_hi:[0,1]
	v_pk_add_f32 v[52:53], v[52:53], v[216:217] op_sel_hi:[1,0] neg_lo:[0,1] neg_hi:[0,1]
	v_pk_add_f32 v[54:55], v[54:55], v[216:217] op_sel_hi:[1,0] neg_lo:[0,1] neg_hi:[0,1]
	v_pk_add_f32 v[56:57], v[56:57], v[216:217] op_sel_hi:[1,0] neg_lo:[0,1] neg_hi:[0,1]
	v_pk_add_f32 v[58:59], v[58:59], v[216:217] op_sel_hi:[1,0] neg_lo:[0,1] neg_hi:[0,1]
	v_pk_mul_f32 v[76:77], v[44:45], v[44:45]
	v_pk_mul_f32 v[136:137], v[46:47], v[46:47]
	v_add_f32_e32 v133, v76, v77
	v_add_f32_e32 v133, v136, v133
	v_add_f32_e32 v133, v137, v133
	v_pk_mul_f32 v[76:77], v[48:49], v[48:49]
	v_pk_mul_f32 v[136:137], v[50:51], v[50:51]
	v_add_f32_e32 v133, v76, v133
	v_add_f32_e32 v133, v77, v133
	v_add_f32_e32 v133, v136, v133
	v_add_f32_e32 v133, v137, v133
	v_pk_mul_f32 v[76:77], v[52:53], v[52:53]
	v_pk_mul_f32 v[136:137], v[54:55], v[54:55]
	v_add_f32_e32 v133, v76, v133
	v_add_f32_e32 v133, v77, v133
	v_add_f32_e32 v133, v136, v133
	v_add_f32_e32 v133, v137, v133
	v_pk_mul_f32 v[76:77], v[56:57], v[56:57]
	v_pk_mul_f32 v[136:137], v[58:59], v[58:59]
	v_add_f32_e32 v133, v76, v133
	v_add_f32_e32 v133, v77, v133
	v_add_f32_e32 v133, v136, v133
	v_add_f32_e32 v133, v137, v133
	s_nop 1
	v_add_f32_dpp v133, v133, v133 quad_perm:[1,0,3,2] row_mask:0xf bank_mask:0xf bound_ctrl:1
	s_nop 1
	v_add_f32_dpp v133, v133, v133 quad_perm:[2,3,0,1] row_mask:0xf bank_mask:0xf bound_ctrl:1
	s_nop 1
	v_add_f32_dpp v133, v133, v133 row_half_mirror row_mask:0xf bank_mask:0xf bound_ctrl:1
	s_nop 1
	v_add_f32_dpp v133, v133, v133 row_mirror row_mask:0xf bank_mask:0xf bound_ctrl:1
	s_nop 1
	v_readlane_b32 s56, v133, 0
	v_readlane_b32 s57, v133, 16
	v_readlane_b32 s58, v133, 32
	v_readlane_b32 s59, v133, 48
	v_mov_b32_e32 v222, s57
	v_mov_b32_e32 v223, s59
	v_add_f32_e32 v222, s56, v222
	v_add_f32_e32 v223, s58, v223
	v_add_f32_e32 v133, v222, v223
	v_fmamk_f32 v133, v133, 0x3a800000, v215
	v_cmp_gt_f32_e32 vcc, s33, v133
	v_mul_f32_e32 v222, 0x4b800000, v133
	s_nop 0
	v_cndmask_b32_e32 v133, v133, v222, vcc
	v_rsq_f32_e32 v133, v133
	s_nop 0
	v_mul_f32_e32 v222, 0x45800000, v133
	v_cndmask_b32_e32 v220, v133, v222, vcc
	v_pk_mul_f32 v[44:45], v[44:45], v[220:221] op_sel_hi:[1,0]
	v_pk_mul_f32 v[46:47], v[46:47], v[220:221] op_sel_hi:[1,0]
	v_pk_mul_f32 v[48:49], v[48:49], v[220:221] op_sel_hi:[1,0]
	v_pk_mul_f32 v[50:51], v[50:51], v[220:221] op_sel_hi:[1,0]
	v_pk_mul_f32 v[52:53], v[52:53], v[220:221] op_sel_hi:[1,0]
	v_pk_mul_f32 v[54:55], v[54:55], v[220:221] op_sel_hi:[1,0]
	v_pk_mul_f32 v[56:57], v[56:57], v[220:221] op_sel_hi:[1,0]
	v_pk_mul_f32 v[58:59], v[58:59], v[220:221] op_sel_hi:[1,0]
	v_pk_fma_f32 v[44:45], v[184:185], v[44:45], v[200:201]
	v_pk_fma_f32 v[46:47], v[186:187], v[46:47], v[202:203]
	v_pk_fma_f32 v[48:49], v[188:189], v[48:49], v[204:205]
	v_pk_fma_f32 v[50:51], v[190:191], v[50:51], v[206:207]
	v_pk_fma_f32 v[52:53], v[192:193], v[52:53], v[226:227]
	v_pk_fma_f32 v[54:55], v[194:195], v[54:55], v[228:229]
	v_pk_fma_f32 v[56:57], v[196:197], v[56:57], v[230:231]
	v_pk_fma_f32 v[58:59], v[198:199], v[58:59], v[232:233]
	global_store_dwordx4 v212, v[44:47], s[46:47] offset:0
	global_store_dwordx4 v212, v[48:51], s[46:47] offset:1024
	global_store_dwordx4 v212, v[52:55], s[46:47] offset:2048
	global_store_dwordx4 v212, v[56:59], s[46:47] offset:3072
	v_cvt_pk_bf16_f32 v44, v44, v45
	v_cvt_pk_bf16_f32 v45, v46, v47
	v_cvt_pk_bf16_f32 v48, v48, v49
	v_cvt_pk_bf16_f32 v49, v50, v51
	v_cvt_pk_bf16_f32 v52, v52, v53
	v_cvt_pk_bf16_f32 v53, v54, v55
	v_cvt_pk_bf16_f32 v56, v56, v57
	v_cvt_pk_bf16_f32 v57, v58, v59
	global_store_dwordx2 v214, v[44:45], s[68:69] offset:0
	global_store_dwordx2 v214, v[48:49], s[68:69] offset:512
	global_store_dwordx2 v214, v[52:53], s[68:69] offset:1024
	global_store_dwordx2 v214, v[56:57], s[68:69] offset:1536
	s_waitcnt vmcnt(40)
	v_pk_add_f32 v[76:77], v[60:61], v[62:63]
	v_pk_add_f32 v[136:137], v[64:65], v[66:67]
	v_pk_add_f32 v[138:139], v[94:95], v[96:97]
	v_pk_add_f32 v[208:209], v[98:99], v[100:101]
	v_pk_add_f32 v[76:77], v[76:77], v[136:137]
	v_pk_add_f32 v[138:139], v[138:139], v[208:209]
	v_pk_add_f32 v[76:77], v[76:77], v[138:139]
	v_add_f32_e32 v131, v76, v77
	s_nop 1
	v_add_f32_dpp v131, v131, v131 quad_perm:[1,0,3,2] row_mask:0xf bank_mask:0xf bound_ctrl:1
	s_nop 1
	v_add_f32_dpp v131, v131, v131 quad_perm:[2,3,0,1] row_mask:0xf bank_mask:0xf bound_ctrl:1
	s_nop 1
	v_add_f32_dpp v131, v131, v131 row_half_mirror row_mask:0xf bank_mask:0xf bound_ctrl:1
	s_nop 1
	v_add_f32_dpp v131, v131, v131 row_mirror row_mask:0xf bank_mask:0xf bound_ctrl:1
	s_nop 1
	v_readlane_b32 s56, v131, 0
	v_readlane_b32 s57, v131, 16
	v_readlane_b32 s58, v131, 32
	v_readlane_b32 s59, v131, 48
	v_mov_b32_e32 v222, s57
	v_mov_b32_e32 v223, s59
	v_add_f32_e32 v222, s56, v222
	v_add_f32_e32 v223, s58, v223
	v_add_f32_e32 v131, v222, v223
	v_mul_f32_e32 v216, 0x3a800000, v131
	v_pk_add_f32 v[60:61], v[60:61], v[216:217] op_sel_hi:[1,0] neg_lo:[0,1] neg_hi:[0,1]
	v_pk_add_f32 v[62:63], v[62:63], v[216:217] op_sel_hi:[1,0] neg_lo:[0,1] neg_hi:[0,1]
	v_pk_add_f32 v[64:65], v[64:65], v[216:217] op_sel_hi:[1,0] neg_lo:[0,1] neg_hi:[0,1]
	v_pk_add_f32 v[66:67], v[66:67], v[216:217] op_sel_hi:[1,0] neg_lo:[0,1] neg_hi:[0,1]
	v_pk_add_f32 v[94:95], v[94:95], v[216:217] op_sel_hi:[1,0] neg_lo:[0,1] neg_hi:[0,1]
	v_pk_add_f32 v[96:97], v[96:97], v[216:217] op_sel_hi:[1,0] neg_lo:[0,1] neg_hi:[0,1]
	v_pk_add_f32 v[98:99], v[98:99], v[216:217] op_sel_hi:[1,0] neg_lo:[0,1] neg_hi:[0,1]
	v_pk_add_f32 v[100:101], v[100:101], v[216:217] op_sel_hi:[1,0] neg_lo:[0,1] neg_hi:[0,1]
	v_pk_mul_f32 v[76:77], v[60:61], v[60:61]
	v_pk_mul_f32 v[136:137], v[62:63], v[62:63]
	v_add_f32_e32 v133, v76, v77
	v_add_f32_e32 v133, v136, v133
	v_add_f32_e32 v133, v137, v133
	v_pk_mul_f32 v[76:77], v[64:65], v[64:65]
	v_pk_mul_f32 v[136:137], v[66:67], v[66:67]
	v_add_f32_e32 v133, v76, v133
	v_add_f32_e32 v133, v77, v133
	v_add_f32_e32 v133, v136, v133
	v_add_f32_e32 v133, v137, v133
	v_pk_mul_f32 v[76:77], v[94:95], v[94:95]
	v_pk_mul_f32 v[136:137], v[96:97], v[96:97]
	v_add_f32_e32 v133, v76, v133
	v_add_f32_e32 v133, v77, v133
	v_add_f32_e32 v133, v136, v133
	v_add_f32_e32 v133, v137, v133
	v_pk_mul_f32 v[76:77], v[98:99], v[98:99]
	v_pk_mul_f32 v[136:137], v[100:101], v[100:101]
	v_add_f32_e32 v133, v76, v133
	v_add_f32_e32 v133, v77, v133
	v_add_f32_e32 v133, v136, v133
	v_add_f32_e32 v133, v137, v133
	s_nop 1
	v_add_f32_dpp v133, v133, v133 quad_perm:[1,0,3,2] row_mask:0xf bank_mask:0xf bound_ctrl:1
	s_nop 1
	v_add_f32_dpp v133, v133, v133 quad_perm:[2,3,0,1] row_mask:0xf bank_mask:0xf bound_ctrl:1
	s_nop 1
	v_add_f32_dpp v133, v133, v133 row_half_mirror row_mask:0xf bank_mask:0xf bound_ctrl:1
	s_nop 1
	v_add_f32_dpp v133, v133, v133 row_mirror row_mask:0xf bank_mask:0xf bound_ctrl:1
	s_nop 1
	v_readlane_b32 s56, v133, 0
	v_readlane_b32 s57, v133, 16
	v_readlane_b32 s58, v133, 32
	v_readlane_b32 s59, v133, 48
	v_mov_b32_e32 v222, s57
	v_mov_b32_e32 v223, s59
	v_add_f32_e32 v222, s56, v222
	v_add_f32_e32 v223, s58, v223
	v_add_f32_e32 v133, v222, v223
	v_fmamk_f32 v133, v133, 0x3a800000, v215
	v_cmp_gt_f32_e32 vcc, s33, v133
	v_mul_f32_e32 v222, 0x4b800000, v133
	s_nop 0
	v_cndmask_b32_e32 v133, v133, v222, vcc
	v_rsq_f32_e32 v133, v133
	s_nop 0
	v_mul_f32_e32 v222, 0x45800000, v133
	v_cndmask_b32_e32 v220, v133, v222, vcc
	v_pk_mul_f32 v[60:61], v[60:61], v[220:221] op_sel_hi:[1,0]
	v_pk_mul_f32 v[62:63], v[62:63], v[220:221] op_sel_hi:[1,0]
	v_pk_mul_f32 v[64:65], v[64:65], v[220:221] op_sel_hi:[1,0]
	v_pk_mul_f32 v[66:67], v[66:67], v[220:221] op_sel_hi:[1,0]
	v_pk_mul_f32 v[94:95], v[94:95], v[220:221] op_sel_hi:[1,0]
	v_pk_mul_f32 v[96:97], v[96:97], v[220:221] op_sel_hi:[1,0]
	v_pk_mul_f32 v[98:99], v[98:99], v[220:221] op_sel_hi:[1,0]
	v_pk_mul_f32 v[100:101], v[100:101], v[220:221] op_sel_hi:[1,0]
	v_pk_fma_f32 v[60:61], v[184:185], v[60:61], v[200:201]
	v_pk_fma_f32 v[62:63], v[186:187], v[62:63], v[202:203]
	v_pk_fma_f32 v[64:65], v[188:189], v[64:65], v[204:205]
	v_pk_fma_f32 v[66:67], v[190:191], v[66:67], v[206:207]
	v_pk_fma_f32 v[94:95], v[192:193], v[94:95], v[226:227]
	v_pk_fma_f32 v[96:97], v[194:195], v[96:97], v[228:229]
	v_pk_fma_f32 v[98:99], v[196:197], v[98:99], v[230:231]
	v_pk_fma_f32 v[100:101], v[198:199], v[100:101], v[232:233]
	global_store_dwordx4 v212, v[60:63], s[48:49] offset:0
	global_store_dwordx4 v212, v[64:67], s[48:49] offset:1024
	global_store_dwordx4 v212, v[94:97], s[48:49] offset:2048
	global_store_dwordx4 v212, v[98:101], s[48:49] offset:3072
	v_cvt_pk_bf16_f32 v60, v60, v61
	v_cvt_pk_bf16_f32 v61, v62, v63
	v_cvt_pk_bf16_f32 v64, v64, v65
	v_cvt_pk_bf16_f32 v65, v66, v67
	v_cvt_pk_bf16_f32 v94, v94, v95
	v_cvt_pk_bf16_f32 v95, v96, v97
	v_cvt_pk_bf16_f32 v98, v98, v99
	v_cvt_pk_bf16_f32 v99, v100, v101
	global_store_dwordx2 v214, v[60:61], s[68:69] offset:2048
	global_store_dwordx2 v214, v[64:65], s[68:69] offset:2560
	global_store_dwordx2 v214, v[94:95], s[68:69] offset:3072
	global_store_dwordx2 v214, v[98:99], s[68:69] offset:3584
	s_waitcnt vmcnt(44)
	v_pk_add_f32 v[76:77], v[102:103], v[104:105]
	v_pk_add_f32 v[136:137], v[106:107], v[108:109]
	v_pk_add_f32 v[138:139], v[110:111], v[112:113]
	v_pk_add_f32 v[208:209], v[114:115], v[116:117]
	v_pk_add_f32 v[76:77], v[76:77], v[136:137]
	v_pk_add_f32 v[138:139], v[138:139], v[208:209]
	v_pk_add_f32 v[76:77], v[76:77], v[138:139]
	v_add_f32_e32 v131, v76, v77
	s_nop 1
	v_add_f32_dpp v131, v131, v131 quad_perm:[1,0,3,2] row_mask:0xf bank_mask:0xf bound_ctrl:1
	s_nop 1
	v_add_f32_dpp v131, v131, v131 quad_perm:[2,3,0,1] row_mask:0xf bank_mask:0xf bound_ctrl:1
	s_nop 1
	v_add_f32_dpp v131, v131, v131 row_half_mirror row_mask:0xf bank_mask:0xf bound_ctrl:1
	s_nop 1
	v_add_f32_dpp v131, v131, v131 row_mirror row_mask:0xf bank_mask:0xf bound_ctrl:1
	s_nop 1
	v_readlane_b32 s56, v131, 0
	v_readlane_b32 s57, v131, 16
	v_readlane_b32 s58, v131, 32
	v_readlane_b32 s59, v131, 48
	v_mov_b32_e32 v222, s57
	v_mov_b32_e32 v223, s59
	v_add_f32_e32 v222, s56, v222
	v_add_f32_e32 v223, s58, v223
	v_add_f32_e32 v131, v222, v223
	v_mul_f32_e32 v216, 0x3a800000, v131
	v_pk_add_f32 v[102:103], v[102:103], v[216:217] op_sel_hi:[1,0] neg_lo:[0,1] neg_hi:[0,1]
	v_pk_add_f32 v[104:105], v[104:105], v[216:217] op_sel_hi:[1,0] neg_lo:[0,1] neg_hi:[0,1]
	v_pk_add_f32 v[106:107], v[106:107], v[216:217] op_sel_hi:[1,0] neg_lo:[0,1] neg_hi:[0,1]
	v_pk_add_f32 v[108:109], v[108:109], v[216:217] op_sel_hi:[1,0] neg_lo:[0,1] neg_hi:[0,1]
	v_pk_add_f32 v[110:111], v[110:111], v[216:217] op_sel_hi:[1,0] neg_lo:[0,1] neg_hi:[0,1]
	v_pk_add_f32 v[112:113], v[112:113], v[216:217] op_sel_hi:[1,0] neg_lo:[0,1] neg_hi:[0,1]
	v_pk_add_f32 v[114:115], v[114:115], v[216:217] op_sel_hi:[1,0] neg_lo:[0,1] neg_hi:[0,1]
	v_pk_add_f32 v[116:117], v[116:117], v[216:217] op_sel_hi:[1,0] neg_lo:[0,1] neg_hi:[0,1]
	v_pk_mul_f32 v[76:77], v[102:103], v[102:103]
	v_pk_mul_f32 v[136:137], v[104:105], v[104:105]
	v_add_f32_e32 v133, v76, v77
	v_add_f32_e32 v133, v136, v133
	v_add_f32_e32 v133, v137, v133
	v_pk_mul_f32 v[76:77], v[106:107], v[106:107]
	v_pk_mul_f32 v[136:137], v[108:109], v[108:109]
	v_add_f32_e32 v133, v76, v133
	v_add_f32_e32 v133, v77, v133
	v_add_f32_e32 v133, v136, v133
	v_add_f32_e32 v133, v137, v133
	v_pk_mul_f32 v[76:77], v[110:111], v[110:111]
	v_pk_mul_f32 v[136:137], v[112:113], v[112:113]
	v_add_f32_e32 v133, v76, v133
	v_add_f32_e32 v133, v77, v133
	v_add_f32_e32 v133, v136, v133
	v_add_f32_e32 v133, v137, v133
	v_pk_mul_f32 v[76:77], v[114:115], v[114:115]
	v_pk_mul_f32 v[136:137], v[116:117], v[116:117]
	v_add_f32_e32 v133, v76, v133
	v_add_f32_e32 v133, v77, v133
	v_add_f32_e32 v133, v136, v133
	v_add_f32_e32 v133, v137, v133
	s_nop 1
	v_add_f32_dpp v133, v133, v133 quad_perm:[1,0,3,2] row_mask:0xf bank_mask:0xf bound_ctrl:1
	s_nop 1
	v_add_f32_dpp v133, v133, v133 quad_perm:[2,3,0,1] row_mask:0xf bank_mask:0xf bound_ctrl:1
	s_nop 1
	v_add_f32_dpp v133, v133, v133 row_half_mirror row_mask:0xf bank_mask:0xf bound_ctrl:1
	s_nop 1
	v_add_f32_dpp v133, v133, v133 row_mirror row_mask:0xf bank_mask:0xf bound_ctrl:1
	s_nop 1
	v_readlane_b32 s56, v133, 0
	v_readlane_b32 s57, v133, 16
	v_readlane_b32 s58, v133, 32
	v_readlane_b32 s59, v133, 48
	v_mov_b32_e32 v222, s57
	v_mov_b32_e32 v223, s59
	v_add_f32_e32 v222, s56, v222
	v_add_f32_e32 v223, s58, v223
	v_add_f32_e32 v133, v222, v223
	v_fmamk_f32 v133, v133, 0x3a800000, v215
	v_cmp_gt_f32_e32 vcc, s33, v133
	v_mul_f32_e32 v222, 0x4b800000, v133
	s_nop 0
	v_cndmask_b32_e32 v133, v133, v222, vcc
	v_rsq_f32_e32 v133, v133
	s_nop 0
	v_mul_f32_e32 v222, 0x45800000, v133
	v_cndmask_b32_e32 v220, v133, v222, vcc
	v_pk_mul_f32 v[102:103], v[102:103], v[220:221] op_sel_hi:[1,0]
	v_pk_mul_f32 v[104:105], v[104:105], v[220:221] op_sel_hi:[1,0]
	v_pk_mul_f32 v[106:107], v[106:107], v[220:221] op_sel_hi:[1,0]
	v_pk_mul_f32 v[108:109], v[108:109], v[220:221] op_sel_hi:[1,0]
	v_pk_mul_f32 v[110:111], v[110:111], v[220:221] op_sel_hi:[1,0]
	v_pk_mul_f32 v[112:113], v[112:113], v[220:221] op_sel_hi:[1,0]
	v_pk_mul_f32 v[114:115], v[114:115], v[220:221] op_sel_hi:[1,0]
	v_pk_mul_f32 v[116:117], v[116:117], v[220:221] op_sel_hi:[1,0]
	v_pk_fma_f32 v[102:103], v[184:185], v[102:103], v[200:201]
	v_pk_fma_f32 v[104:105], v[186:187], v[104:105], v[202:203]
	v_pk_fma_f32 v[106:107], v[188:189], v[106:107], v[204:205]
	v_pk_fma_f32 v[108:109], v[190:191], v[108:109], v[206:207]
	v_pk_fma_f32 v[110:111], v[192:193], v[110:111], v[226:227]
	v_pk_fma_f32 v[112:113], v[194:195], v[112:113], v[228:229]
	v_pk_fma_f32 v[114:115], v[196:197], v[114:115], v[230:231]
	v_pk_fma_f32 v[116:117], v[198:199], v[116:117], v[232:233]
	global_store_dwordx4 v212, v[102:105], s[50:51] offset:0
	global_store_dwordx4 v212, v[106:109], s[50:51] offset:1024
	global_store_dwordx4 v212, v[110:113], s[50:51] offset:2048
	global_store_dwordx4 v212, v[114:117], s[50:51] offset:3072
	v_cvt_pk_bf16_f32 v102, v102, v103
	v_cvt_pk_bf16_f32 v103, v104, v105
	v_cvt_pk_bf16_f32 v106, v106, v107
	v_cvt_pk_bf16_f32 v107, v108, v109
	v_cvt_pk_bf16_f32 v110, v110, v111
	v_cvt_pk_bf16_f32 v111, v112, v113
	v_cvt_pk_bf16_f32 v114, v114, v115
	v_cvt_pk_bf16_f32 v115, v116, v117
	global_store_dwordx2 v214, v[102:103], s[70:71] offset:0
	global_store_dwordx2 v214, v[106:107], s[70:71] offset:512
	global_store_dwordx2 v214, v[110:111], s[70:71] offset:1024
	global_store_dwordx2 v214, v[114:115], s[70:71] offset:1536
	s_waitcnt vmcnt(48)
	v_pk_add_f32 v[76:77], v[118:119], v[120:121]
	v_pk_add_f32 v[136:137], v[122:123], v[124:125]
	v_pk_add_f32 v[138:139], v[144:145], v[146:147]
	v_pk_add_f32 v[208:209], v[148:149], v[150:151]
	v_pk_add_f32 v[76:77], v[76:77], v[136:137]
	v_pk_add_f32 v[138:139], v[138:139], v[208:209]
	v_pk_add_f32 v[76:77], v[76:77], v[138:139]
	v_add_f32_e32 v131, v76, v77
	s_nop 1
	v_add_f32_dpp v131, v131, v131 quad_perm:[1,0,3,2] row_mask:0xf bank_mask:0xf bound_ctrl:1
	s_nop 1
	v_add_f32_dpp v131, v131, v131 quad_perm:[2,3,0,1] row_mask:0xf bank_mask:0xf bound_ctrl:1
	s_nop 1
	v_add_f32_dpp v131, v131, v131 row_half_mirror row_mask:0xf bank_mask:0xf bound_ctrl:1
	s_nop 1
	v_add_f32_dpp v131, v131, v131 row_mirror row_mask:0xf bank_mask:0xf bound_ctrl:1
	s_nop 1
	v_readlane_b32 s56, v131, 0
	v_readlane_b32 s57, v131, 16
	v_readlane_b32 s58, v131, 32
	v_readlane_b32 s59, v131, 48
	v_mov_b32_e32 v222, s57
	v_mov_b32_e32 v223, s59
	v_add_f32_e32 v222, s56, v222
	v_add_f32_e32 v223, s58, v223
	v_add_f32_e32 v131, v222, v223
	v_mul_f32_e32 v216, 0x3a800000, v131
	v_pk_add_f32 v[118:119], v[118:119], v[216:217] op_sel_hi:[1,0] neg_lo:[0,1] neg_hi:[0,1]
	v_pk_add_f32 v[120:121], v[120:121], v[216:217] op_sel_hi:[1,0] neg_lo:[0,1] neg_hi:[0,1]
	v_pk_add_f32 v[122:123], v[122:123], v[216:217] op_sel_hi:[1,0] neg_lo:[0,1] neg_hi:[0,1]
	v_pk_add_f32 v[124:125], v[124:125], v[216:217] op_sel_hi:[1,0] neg_lo:[0,1] neg_hi:[0,1]
	v_pk_add_f32 v[144:145], v[144:145], v[216:217] op_sel_hi:[1,0] neg_lo:[0,1] neg_hi:[0,1]
	v_pk_add_f32 v[146:147], v[146:147], v[216:217] op_sel_hi:[1,0] neg_lo:[0,1] neg_hi:[0,1]
	v_pk_add_f32 v[148:149], v[148:149], v[216:217] op_sel_hi:[1,0] neg_lo:[0,1] neg_hi:[0,1]
	v_pk_add_f32 v[150:151], v[150:151], v[216:217] op_sel_hi:[1,0] neg_lo:[0,1] neg_hi:[0,1]
	v_pk_mul_f32 v[76:77], v[118:119], v[118:119]
	v_pk_mul_f32 v[136:137], v[120:121], v[120:121]
	v_add_f32_e32 v133, v76, v77
	v_add_f32_e32 v133, v136, v133
	v_add_f32_e32 v133, v137, v133
	v_pk_mul_f32 v[76:77], v[122:123], v[122:123]
	v_pk_mul_f32 v[136:137], v[124:125], v[124:125]
	v_add_f32_e32 v133, v76, v133
	v_add_f32_e32 v133, v77, v133
	v_add_f32_e32 v133, v136, v133
	v_add_f32_e32 v133, v137, v133
	v_pk_mul_f32 v[76:77], v[144:145], v[144:145]
	v_pk_mul_f32 v[136:137], v[146:147], v[146:147]
	v_add_f32_e32 v133, v76, v133
	v_add_f32_e32 v133, v77, v133
	v_add_f32_e32 v133, v136, v133
	v_add_f32_e32 v133, v137, v133
	v_pk_mul_f32 v[76:77], v[148:149], v[148:149]
	v_pk_mul_f32 v[136:137], v[150:151], v[150:151]
	v_add_f32_e32 v133, v76, v133
	v_add_f32_e32 v133, v77, v133
	v_add_f32_e32 v133, v136, v133
	v_add_f32_e32 v133, v137, v133
	s_nop 1
	v_add_f32_dpp v133, v133, v133 quad_perm:[1,0,3,2] row_mask:0xf bank_mask:0xf bound_ctrl:1
	s_nop 1
	v_add_f32_dpp v133, v133, v133 quad_perm:[2,3,0,1] row_mask:0xf bank_mask:0xf bound_ctrl:1
	s_nop 1
	v_add_f32_dpp v133, v133, v133 row_half_mirror row_mask:0xf bank_mask:0xf bound_ctrl:1
	s_nop 1
	v_add_f32_dpp v133, v133, v133 row_mirror row_mask:0xf bank_mask:0xf bound_ctrl:1
	s_nop 1
	v_readlane_b32 s56, v133, 0
	v_readlane_b32 s57, v133, 16
	v_readlane_b32 s58, v133, 32
	v_readlane_b32 s59, v133, 48
	v_mov_b32_e32 v222, s57
	v_mov_b32_e32 v223, s59
	v_add_f32_e32 v222, s56, v222
	v_add_f32_e32 v223, s58, v223
	v_add_f32_e32 v133, v222, v223
	v_fmamk_f32 v133, v133, 0x3a800000, v215
	v_cmp_gt_f32_e32 vcc, s33, v133
	v_mul_f32_e32 v222, 0x4b800000, v133
	s_nop 0
	v_cndmask_b32_e32 v133, v133, v222, vcc
	v_rsq_f32_e32 v133, v133
	s_nop 0
	v_mul_f32_e32 v222, 0x45800000, v133
	v_cndmask_b32_e32 v220, v133, v222, vcc
	v_pk_mul_f32 v[118:119], v[118:119], v[220:221] op_sel_hi:[1,0]
	v_pk_mul_f32 v[120:121], v[120:121], v[220:221] op_sel_hi:[1,0]
	v_pk_mul_f32 v[122:123], v[122:123], v[220:221] op_sel_hi:[1,0]
	v_pk_mul_f32 v[124:125], v[124:125], v[220:221] op_sel_hi:[1,0]
	v_pk_mul_f32 v[144:145], v[144:145], v[220:221] op_sel_hi:[1,0]
	v_pk_mul_f32 v[146:147], v[146:147], v[220:221] op_sel_hi:[1,0]
	v_pk_mul_f32 v[148:149], v[148:149], v[220:221] op_sel_hi:[1,0]
	v_pk_mul_f32 v[150:151], v[150:151], v[220:221] op_sel_hi:[1,0]
	v_pk_fma_f32 v[118:119], v[184:185], v[118:119], v[200:201]
	v_pk_fma_f32 v[120:121], v[186:187], v[120:121], v[202:203]
	v_pk_fma_f32 v[122:123], v[188:189], v[122:123], v[204:205]
	v_pk_fma_f32 v[124:125], v[190:191], v[124:125], v[206:207]
	v_pk_fma_f32 v[144:145], v[192:193], v[144:145], v[226:227]
	v_pk_fma_f32 v[146:147], v[194:195], v[146:147], v[228:229]
	v_pk_fma_f32 v[148:149], v[196:197], v[148:149], v[230:231]
	v_pk_fma_f32 v[150:151], v[198:199], v[150:151], v[232:233]
	global_store_dwordx4 v212, v[118:121], s[52:53] offset:0
	global_store_dwordx4 v212, v[122:125], s[52:53] offset:1024
	global_store_dwordx4 v212, v[144:147], s[52:53] offset:2048
	global_store_dwordx4 v212, v[148:151], s[52:53] offset:3072
	v_cvt_pk_bf16_f32 v118, v118, v119
	v_cvt_pk_bf16_f32 v119, v120, v121
	v_cvt_pk_bf16_f32 v122, v122, v123
	v_cvt_pk_bf16_f32 v123, v124, v125
	v_cvt_pk_bf16_f32 v144, v144, v145
	v_cvt_pk_bf16_f32 v145, v146, v147
	v_cvt_pk_bf16_f32 v148, v148, v149
	v_cvt_pk_bf16_f32 v149, v150, v151
	global_store_dwordx2 v214, v[118:119], s[70:71] offset:2048
	global_store_dwordx2 v214, v[122:123], s[70:71] offset:2560
	global_store_dwordx2 v214, v[144:145], s[70:71] offset:3072
	global_store_dwordx2 v214, v[148:149], s[70:71] offset:3584
	s_waitcnt vmcnt(52)
	v_pk_add_f32 v[76:77], v[152:153], v[154:155]
	v_pk_add_f32 v[136:137], v[156:157], v[158:159]
	v_pk_add_f32 v[138:139], v[160:161], v[162:163]
	v_pk_add_f32 v[208:209], v[164:165], v[166:167]
	v_pk_add_f32 v[76:77], v[76:77], v[136:137]
	v_pk_add_f32 v[138:139], v[138:139], v[208:209]
	v_pk_add_f32 v[76:77], v[76:77], v[138:139]
	v_add_f32_e32 v131, v76, v77
	s_nop 1
	v_add_f32_dpp v131, v131, v131 quad_perm:[1,0,3,2] row_mask:0xf bank_mask:0xf bound_ctrl:1
	s_nop 1
	v_add_f32_dpp v131, v131, v131 quad_perm:[2,3,0,1] row_mask:0xf bank_mask:0xf bound_ctrl:1
	s_nop 1
	v_add_f32_dpp v131, v131, v131 row_half_mirror row_mask:0xf bank_mask:0xf bound_ctrl:1
	s_nop 1
	v_add_f32_dpp v131, v131, v131 row_mirror row_mask:0xf bank_mask:0xf bound_ctrl:1
	s_nop 1
	v_readlane_b32 s56, v131, 0
	v_readlane_b32 s57, v131, 16
	v_readlane_b32 s58, v131, 32
	v_readlane_b32 s59, v131, 48
	v_mov_b32_e32 v222, s57
	v_mov_b32_e32 v223, s59
	v_add_f32_e32 v222, s56, v222
	v_add_f32_e32 v223, s58, v223
	v_add_f32_e32 v131, v222, v223
	v_mul_f32_e32 v216, 0x3a800000, v131
	v_pk_add_f32 v[152:153], v[152:153], v[216:217] op_sel_hi:[1,0] neg_lo:[0,1] neg_hi:[0,1]
	v_pk_add_f32 v[154:155], v[154:155], v[216:217] op_sel_hi:[1,0] neg_lo:[0,1] neg_hi:[0,1]
	v_pk_add_f32 v[156:157], v[156:157], v[216:217] op_sel_hi:[1,0] neg_lo:[0,1] neg_hi:[0,1]
	v_pk_add_f32 v[158:159], v[158:159], v[216:217] op_sel_hi:[1,0] neg_lo:[0,1] neg_hi:[0,1]
	v_pk_add_f32 v[160:161], v[160:161], v[216:217] op_sel_hi:[1,0] neg_lo:[0,1] neg_hi:[0,1]
	v_pk_add_f32 v[162:163], v[162:163], v[216:217] op_sel_hi:[1,0] neg_lo:[0,1] neg_hi:[0,1]
	v_pk_add_f32 v[164:165], v[164:165], v[216:217] op_sel_hi:[1,0] neg_lo:[0,1] neg_hi:[0,1]
	v_pk_add_f32 v[166:167], v[166:167], v[216:217] op_sel_hi:[1,0] neg_lo:[0,1] neg_hi:[0,1]
	v_pk_mul_f32 v[76:77], v[152:153], v[152:153]
	v_pk_mul_f32 v[136:137], v[154:155], v[154:155]
	v_add_f32_e32 v133, v76, v77
	v_add_f32_e32 v133, v136, v133
	v_add_f32_e32 v133, v137, v133
	v_pk_mul_f32 v[76:77], v[156:157], v[156:157]
	v_pk_mul_f32 v[136:137], v[158:159], v[158:159]
	v_add_f32_e32 v133, v76, v133
	v_add_f32_e32 v133, v77, v133
	v_add_f32_e32 v133, v136, v133
	v_add_f32_e32 v133, v137, v133
	v_pk_mul_f32 v[76:77], v[160:161], v[160:161]
	v_pk_mul_f32 v[136:137], v[162:163], v[162:163]
	v_add_f32_e32 v133, v76, v133
	v_add_f32_e32 v133, v77, v133
	v_add_f32_e32 v133, v136, v133
	v_add_f32_e32 v133, v137, v133
	v_pk_mul_f32 v[76:77], v[164:165], v[164:165]
	v_pk_mul_f32 v[136:137], v[166:167], v[166:167]
	v_add_f32_e32 v133, v76, v133
	v_add_f32_e32 v133, v77, v133
	v_add_f32_e32 v133, v136, v133
	v_add_f32_e32 v133, v137, v133
	s_nop 1
	v_add_f32_dpp v133, v133, v133 quad_perm:[1,0,3,2] row_mask:0xf bank_mask:0xf bound_ctrl:1
	s_nop 1
	v_add_f32_dpp v133, v133, v133 quad_perm:[2,3,0,1] row_mask:0xf bank_mask:0xf bound_ctrl:1
	s_nop 1
	v_add_f32_dpp v133, v133, v133 row_half_mirror row_mask:0xf bank_mask:0xf bound_ctrl:1
	s_nop 1
	v_add_f32_dpp v133, v133, v133 row_mirror row_mask:0xf bank_mask:0xf bound_ctrl:1
	s_nop 1
	v_readlane_b32 s56, v133, 0
	v_readlane_b32 s57, v133, 16
	v_readlane_b32 s58, v133, 32
	v_readlane_b32 s59, v133, 48
	v_mov_b32_e32 v222, s57
	v_mov_b32_e32 v223, s59
	v_add_f32_e32 v222, s56, v222
	v_add_f32_e32 v223, s58, v223
	v_add_f32_e32 v133, v222, v223
	v_fmamk_f32 v133, v133, 0x3a800000, v215
	v_cmp_gt_f32_e32 vcc, s33, v133
	v_mul_f32_e32 v222, 0x4b800000, v133
	s_nop 0
	v_cndmask_b32_e32 v133, v133, v222, vcc
	v_rsq_f32_e32 v133, v133
	s_nop 0
	v_mul_f32_e32 v222, 0x45800000, v133
	v_cndmask_b32_e32 v220, v133, v222, vcc
	v_pk_mul_f32 v[152:153], v[152:153], v[220:221] op_sel_hi:[1,0]
	v_pk_mul_f32 v[154:155], v[154:155], v[220:221] op_sel_hi:[1,0]
	v_pk_mul_f32 v[156:157], v[156:157], v[220:221] op_sel_hi:[1,0]
	v_pk_mul_f32 v[158:159], v[158:159], v[220:221] op_sel_hi:[1,0]
	v_pk_mul_f32 v[160:161], v[160:161], v[220:221] op_sel_hi:[1,0]
	v_pk_mul_f32 v[162:163], v[162:163], v[220:221] op_sel_hi:[1,0]
	v_pk_mul_f32 v[164:165], v[164:165], v[220:221] op_sel_hi:[1,0]
	v_pk_mul_f32 v[166:167], v[166:167], v[220:221] op_sel_hi:[1,0]
	v_pk_fma_f32 v[152:153], v[184:185], v[152:153], v[200:201]
	v_pk_fma_f32 v[154:155], v[186:187], v[154:155], v[202:203]
	v_pk_fma_f32 v[156:157], v[188:189], v[156:157], v[204:205]
	v_pk_fma_f32 v[158:159], v[190:191], v[158:159], v[206:207]
	v_pk_fma_f32 v[160:161], v[192:193], v[160:161], v[226:227]
	v_pk_fma_f32 v[162:163], v[194:195], v[162:163], v[228:229]
	v_pk_fma_f32 v[164:165], v[196:197], v[164:165], v[230:231]
	v_pk_fma_f32 v[166:167], v[198:199], v[166:167], v[232:233]
	global_store_dwordx4 v212, v[152:155], s[62:63] offset:0
	global_store_dwordx4 v212, v[156:159], s[62:63] offset:1024
	global_store_dwordx4 v212, v[160:163], s[62:63] offset:2048
	global_store_dwordx4 v212, v[164:167], s[62:63] offset:3072
	v_cvt_pk_bf16_f32 v152, v152, v153
	v_cvt_pk_bf16_f32 v153, v154, v155
	v_cvt_pk_bf16_f32 v156, v156, v157
	v_cvt_pk_bf16_f32 v157, v158, v159
	v_cvt_pk_bf16_f32 v160, v160, v161
	v_cvt_pk_bf16_f32 v161, v162, v163
	v_cvt_pk_bf16_f32 v164, v164, v165
	v_cvt_pk_bf16_f32 v165, v166, v167
	global_store_dwordx2 v214, v[152:153], s[72:73] offset:0
	global_store_dwordx2 v214, v[156:157], s[72:73] offset:512
	global_store_dwordx2 v214, v[160:161], s[72:73] offset:1024
	global_store_dwordx2 v214, v[164:165], s[72:73] offset:1536
	s_waitcnt vmcnt(56)
	v_pk_add_f32 v[76:77], v[168:169], v[170:171]
	v_pk_add_f32 v[136:137], v[172:173], v[174:175]
	v_pk_add_f32 v[138:139], v[176:177], v[178:179]
	v_pk_add_f32 v[208:209], v[180:181], v[182:183]
	v_pk_add_f32 v[76:77], v[76:77], v[136:137]
	v_pk_add_f32 v[138:139], v[138:139], v[208:209]
	v_pk_add_f32 v[76:77], v[76:77], v[138:139]
	v_add_f32_e32 v131, v76, v77
	s_nop 1
	v_add_f32_dpp v131, v131, v131 quad_perm:[1,0,3,2] row_mask:0xf bank_mask:0xf bound_ctrl:1
	s_nop 1
	v_add_f32_dpp v131, v131, v131 quad_perm:[2,3,0,1] row_mask:0xf bank_mask:0xf bound_ctrl:1
	s_nop 1
	v_add_f32_dpp v131, v131, v131 row_half_mirror row_mask:0xf bank_mask:0xf bound_ctrl:1
	s_nop 1
	v_add_f32_dpp v131, v131, v131 row_mirror row_mask:0xf bank_mask:0xf bound_ctrl:1
	s_nop 1
	v_readlane_b32 s56, v131, 0
	v_readlane_b32 s57, v131, 16
	v_readlane_b32 s58, v131, 32
	v_readlane_b32 s59, v131, 48
	v_mov_b32_e32 v222, s57
	v_mov_b32_e32 v223, s59
	v_add_f32_e32 v222, s56, v222
	v_add_f32_e32 v223, s58, v223
	v_add_f32_e32 v131, v222, v223
	v_mul_f32_e32 v216, 0x3a800000, v131
	v_pk_add_f32 v[168:169], v[168:169], v[216:217] op_sel_hi:[1,0] neg_lo:[0,1] neg_hi:[0,1]
	v_pk_add_f32 v[170:171], v[170:171], v[216:217] op_sel_hi:[1,0] neg_lo:[0,1] neg_hi:[0,1]
	v_pk_add_f32 v[172:173], v[172:173], v[216:217] op_sel_hi:[1,0] neg_lo:[0,1] neg_hi:[0,1]
	v_pk_add_f32 v[174:175], v[174:175], v[216:217] op_sel_hi:[1,0] neg_lo:[0,1] neg_hi:[0,1]
	v_pk_add_f32 v[176:177], v[176:177], v[216:217] op_sel_hi:[1,0] neg_lo:[0,1] neg_hi:[0,1]
	v_pk_add_f32 v[178:179], v[178:179], v[216:217] op_sel_hi:[1,0] neg_lo:[0,1] neg_hi:[0,1]
	v_pk_add_f32 v[180:181], v[180:181], v[216:217] op_sel_hi:[1,0] neg_lo:[0,1] neg_hi:[0,1]
	v_pk_add_f32 v[182:183], v[182:183], v[216:217] op_sel_hi:[1,0] neg_lo:[0,1] neg_hi:[0,1]
	v_pk_mul_f32 v[76:77], v[168:169], v[168:169]
	v_pk_mul_f32 v[136:137], v[170:171], v[170:171]
	v_add_f32_e32 v133, v76, v77
	v_add_f32_e32 v133, v136, v133
	v_add_f32_e32 v133, v137, v133
	v_pk_mul_f32 v[76:77], v[172:173], v[172:173]
	v_pk_mul_f32 v[136:137], v[174:175], v[174:175]
	v_add_f32_e32 v133, v76, v133
	v_add_f32_e32 v133, v77, v133
	v_add_f32_e32 v133, v136, v133
	v_add_f32_e32 v133, v137, v133
	v_pk_mul_f32 v[76:77], v[176:177], v[176:177]
	v_pk_mul_f32 v[136:137], v[178:179], v[178:179]
	v_add_f32_e32 v133, v76, v133
	v_add_f32_e32 v133, v77, v133
	v_add_f32_e32 v133, v136, v133
	v_add_f32_e32 v133, v137, v133
	v_pk_mul_f32 v[76:77], v[180:181], v[180:181]
	v_pk_mul_f32 v[136:137], v[182:183], v[182:183]
	v_add_f32_e32 v133, v76, v133
	v_add_f32_e32 v133, v77, v133
	v_add_f32_e32 v133, v136, v133
	v_add_f32_e32 v133, v137, v133
	s_nop 1
	v_add_f32_dpp v133, v133, v133 quad_perm:[1,0,3,2] row_mask:0xf bank_mask:0xf bound_ctrl:1
	s_nop 1
	v_add_f32_dpp v133, v133, v133 quad_perm:[2,3,0,1] row_mask:0xf bank_mask:0xf bound_ctrl:1
	s_nop 1
	v_add_f32_dpp v133, v133, v133 row_half_mirror row_mask:0xf bank_mask:0xf bound_ctrl:1
	s_nop 1
	v_add_f32_dpp v133, v133, v133 row_mirror row_mask:0xf bank_mask:0xf bound_ctrl:1
	s_nop 1
	v_readlane_b32 s56, v133, 0
	v_readlane_b32 s57, v133, 16
	v_readlane_b32 s58, v133, 32
	v_readlane_b32 s59, v133, 48
	v_mov_b32_e32 v222, s57
	v_mov_b32_e32 v223, s59
	v_add_f32_e32 v222, s56, v222
	v_add_f32_e32 v223, s58, v223
	v_add_f32_e32 v133, v222, v223
	v_fmamk_f32 v133, v133, 0x3a800000, v215
	v_cmp_gt_f32_e32 vcc, s33, v133
	v_mul_f32_e32 v222, 0x4b800000, v133
	s_nop 0
	v_cndmask_b32_e32 v133, v133, v222, vcc
	v_rsq_f32_e32 v133, v133
	s_nop 0
	v_mul_f32_e32 v222, 0x45800000, v133
	v_cndmask_b32_e32 v220, v133, v222, vcc
	v_pk_mul_f32 v[168:169], v[168:169], v[220:221] op_sel_hi:[1,0]
	v_pk_mul_f32 v[170:171], v[170:171], v[220:221] op_sel_hi:[1,0]
	v_pk_mul_f32 v[172:173], v[172:173], v[220:221] op_sel_hi:[1,0]
	v_pk_mul_f32 v[174:175], v[174:175], v[220:221] op_sel_hi:[1,0]
	v_pk_mul_f32 v[176:177], v[176:177], v[220:221] op_sel_hi:[1,0]
	v_pk_mul_f32 v[178:179], v[178:179], v[220:221] op_sel_hi:[1,0]
	v_pk_mul_f32 v[180:181], v[180:181], v[220:221] op_sel_hi:[1,0]
	v_pk_mul_f32 v[182:183], v[182:183], v[220:221] op_sel_hi:[1,0]
	v_pk_fma_f32 v[168:169], v[184:185], v[168:169], v[200:201]
	v_pk_fma_f32 v[170:171], v[186:187], v[170:171], v[202:203]
	v_pk_fma_f32 v[172:173], v[188:189], v[172:173], v[204:205]
	v_pk_fma_f32 v[174:175], v[190:191], v[174:175], v[206:207]
	v_pk_fma_f32 v[176:177], v[192:193], v[176:177], v[226:227]
	v_pk_fma_f32 v[178:179], v[194:195], v[178:179], v[228:229]
	v_pk_fma_f32 v[180:181], v[196:197], v[180:181], v[230:231]
	v_pk_fma_f32 v[182:183], v[198:199], v[182:183], v[232:233]
	global_store_dwordx4 v212, v[168:171], s[64:65] offset:0
	global_store_dwordx4 v212, v[172:175], s[64:65] offset:1024
	global_store_dwordx4 v212, v[176:179], s[64:65] offset:2048
	global_store_dwordx4 v212, v[180:183], s[64:65] offset:3072
	v_cvt_pk_bf16_f32 v168, v168, v169
	v_cvt_pk_bf16_f32 v169, v170, v171
	v_cvt_pk_bf16_f32 v172, v172, v173
	v_cvt_pk_bf16_f32 v173, v174, v175
	v_cvt_pk_bf16_f32 v176, v176, v177
	v_cvt_pk_bf16_f32 v177, v178, v179
	v_cvt_pk_bf16_f32 v180, v180, v181
	v_cvt_pk_bf16_f32 v181, v182, v183
	global_store_dwordx2 v214, v[168:169], s[72:73] offset:2048
	global_store_dwordx2 v214, v[172:173], s[72:73] offset:2560
	global_store_dwordx2 v214, v[176:177], s[72:73] offset:3072
	global_store_dwordx2 v214, v[180:181], s[72:73] offset:3584
	s_xor_b64 s[20:21], exec, -1
	s_branch .LBB0_1609
